# P9: accumulator zeroing removed (first dword uses non-accumulating v_dot4_i32_i8 with src2=0, 32 fewer VALU per token), exact
# baseline (speedup 1.0000x reference)
; DI void wave_lds_sync() { asm volatile("s_waitcnt lgkmcnt(0)" ::: "memory"); __builtin_amdgcn_wave_barrier(); }
; DI void phase9(const Params& p, char* smem, int rep) {
;     ...
;       const int tok = __builtin_amdgcn_readfirstlane(c * 16 + w * 4 + t);
;       const int i0 = IDS[(size_t)tok * 128 + lane], i1 = IDS[(size_t)tok * 128 + 64 + lane];
;       const u32x4 hq = *(const u32x4*)(H2Q + (size_t)tok * D_ + s * 256 + l15 * 16);
;       wave_lds_sync();
;       lw[(lane & 3) * 32 + (lane >> 2)] = i0;
;       lw[(lane & 3) * 32 + 16 + (lane >> 2)] = i1;
;       wave_lds_sync();
;       const unsigned char* ub = U8 + s * 256 + l15 * 16;
; #pragma unroll
;       for (int batch = 0; batch < 2; ++batch) {
;         int ida[16];
; #pragma unroll
;         for (int q = 0; q < 4; ++q) { const int4 v = *(const int4*)(lw + g * 32 + batch * 16 + q * 4); ida[q * 4] = v.x; ida[q * 4 + 1] = v.y; ida[q * 4 + 2] = v.z; ida[q * 4 + 3] = v.w; }
;         u32x4 rows[16];
; #pragma unroll
;         for (int k = 0; k < 16; ++k) rows[k] = *(const u32x4*)(ub + (size_t)ida[k] * 2048);
;         int part[16];
; #pragma unroll
;         for (int k = 0; k < 16; ++k) {
;           int acc = 0;
; #pragma unroll
;           for (int d = 0; d < 4; ++d) acc = __builtin_amdgcn_sdot4((int)rows[k][d], (int)hq[d], acc, false);
.Lp9_body:
	s_add_i32 s36, s34, 0
	s_lshl_b32 s46, s36, 9
	s_add_i32 s46, s46, s24
	s_add_i32 s37, s34, 1
	s_lshl_b32 s47, s37, 9
	s_add_u32 s42, s6, s47
	s_addc_u32 s43, s7, 0
	s_lshl_b32 s47, s37, 11
	s_add_u32 s44, s22, s47
	s_addc_u32 s45, s23, 0
	global_load_dword v10, v3, s[42:43]
	global_load_dword v11, v3, s[42:43] offset:256
	global_load_dwordx4 v[16:19], v2, s[44:45]
	s_waitcnt lgkmcnt(0)
	v_lshl_add_u32 v20, v20, 11, v2
	v_lshl_add_u32 v21, v21, 11, v2
	v_lshl_add_u32 v22, v22, 11, v2
	v_lshl_add_u32 v23, v23, 11, v2
	v_lshl_add_u32 v24, v24, 11, v2
	v_lshl_add_u32 v25, v25, 11, v2
	v_lshl_add_u32 v26, v26, 11, v2
	v_lshl_add_u32 v27, v27, 11, v2
	v_lshl_add_u32 v28, v28, 11, v2
	v_lshl_add_u32 v29, v29, 11, v2
	v_lshl_add_u32 v30, v30, 11, v2
	v_lshl_add_u32 v31, v31, 11, v2
	v_lshl_add_u32 v32, v32, 11, v2
	v_lshl_add_u32 v33, v33, 11, v2
	v_lshl_add_u32 v34, v34, 11, v2
	v_lshl_add_u32 v35, v35, 11, v2
	v_lshl_add_u32 v36, v36, 11, v2
	v_lshl_add_u32 v37, v37, 11, v2
	v_lshl_add_u32 v38, v38, 11, v2
	v_lshl_add_u32 v39, v39, 11, v2
	v_lshl_add_u32 v40, v40, 11, v2
	v_lshl_add_u32 v41, v41, 11, v2
	v_lshl_add_u32 v42, v42, 11, v2
	v_lshl_add_u32 v43, v43, 11, v2
	v_lshl_add_u32 v44, v44, 11, v2
	v_lshl_add_u32 v45, v45, 11, v2
	v_lshl_add_u32 v46, v46, 11, v2
	v_lshl_add_u32 v47, v47, 11, v2
	v_lshl_add_u32 v48, v48, 11, v2
	v_lshl_add_u32 v49, v49, 11, v2
	v_lshl_add_u32 v50, v50, 11, v2
	v_lshl_add_u32 v51, v51, 11, v2
	global_load_dwordx4 v[84:87], v20, s[20:21]
	global_load_dwordx4 v[88:91], v21, s[20:21]
	global_load_dwordx4 v[92:95], v22, s[20:21]
	global_load_dwordx4 v[96:99], v23, s[20:21]
	global_load_dwordx4 v[100:103], v24, s[20:21]
	global_load_dwordx4 v[104:107], v25, s[20:21]
	global_load_dwordx4 v[108:111], v26, s[20:21]
	global_load_dwordx4 v[112:115], v27, s[20:21]
	global_load_dwordx4 v[116:119], v28, s[20:21]
	global_load_dwordx4 v[120:123], v29, s[20:21]
	global_load_dwordx4 v[124:127], v30, s[20:21]
	global_load_dwordx4 v[128:131], v31, s[20:21]
	global_load_dwordx4 v[132:135], v32, s[20:21]
	global_load_dwordx4 v[136:139], v33, s[20:21]
	global_load_dwordx4 v[140:143], v34, s[20:21]
	global_load_dwordx4 v[144:147], v35, s[20:21]
	global_load_dwordx4 v[148:151], v36, s[20:21]
	global_load_dwordx4 v[152:155], v37, s[20:21]
	global_load_dwordx4 v[156:159], v38, s[20:21]
	global_load_dwordx4 v[160:163], v39, s[20:21]
	global_load_dwordx4 v[164:167], v40, s[20:21]
	global_load_dwordx4 v[168:171], v41, s[20:21]
	global_load_dwordx4 v[172:175], v42, s[20:21]
	global_load_dwordx4 v[176:179], v43, s[20:21]
	global_load_dwordx4 v[180:183], v44, s[20:21]
	global_load_dwordx4 v[184:187], v45, s[20:21]
	global_load_dwordx4 v[190:193], v46, s[20:21]
	global_load_dwordx4 v[194:197], v47, s[20:21]
	global_load_dwordx4 v[198:201], v48, s[20:21]
	global_load_dwordx4 v[202:205], v49, s[20:21]
	global_load_dwordx4 v[206:209], v50, s[20:21]
	global_load_dwordx4 v[210:213], v51, s[20:21]
	s_waitcnt vmcnt(31)
	v_dot4_i32_i8 v52, v84, v12, 0
	s_waitcnt vmcnt(30)
	v_dot4_i32_i8 v53, v88, v12, 0
	s_waitcnt vmcnt(29)
	v_dot4_i32_i8 v54, v92, v12, 0
	s_waitcnt vmcnt(28)
	v_dot4_i32_i8 v55, v96, v12, 0
	s_waitcnt vmcnt(27)
	v_dot4_i32_i8 v56, v100, v12, 0
	s_waitcnt vmcnt(26)
	v_dot4_i32_i8 v57, v104, v12, 0
	s_waitcnt vmcnt(25)
	v_dot4_i32_i8 v58, v108, v12, 0
	s_waitcnt vmcnt(24)
	v_dot4_i32_i8 v59, v112, v12, 0
	s_waitcnt vmcnt(23)
	v_dot4_i32_i8 v60, v116, v12, 0
	s_waitcnt vmcnt(22)
	v_dot4_i32_i8 v61, v120, v12, 0
	s_waitcnt vmcnt(21)
	v_dot4_i32_i8 v62, v124, v12, 0
	s_waitcnt vmcnt(20)
	v_dot4_i32_i8 v63, v128, v12, 0
	s_waitcnt vmcnt(19)
	v_dot4_i32_i8 v64, v132, v12, 0
	s_waitcnt vmcnt(18)
	v_dot4_i32_i8 v65, v136, v12, 0
	s_waitcnt vmcnt(17)
	v_dot4_i32_i8 v66, v140, v12, 0
	s_waitcnt vmcnt(16)
	v_dot4_i32_i8 v67, v144, v12, 0
	v_dot4c_i32_i8_e32 v52, v85, v13
	v_dot4c_i32_i8_e32 v53, v89, v13
	v_dot4c_i32_i8_e32 v54, v93, v13
	v_dot4c_i32_i8_e32 v55, v97, v13
	v_dot4c_i32_i8_e32 v56, v101, v13
	v_dot4c_i32_i8_e32 v57, v105, v13
	v_dot4c_i32_i8_e32 v58, v109, v13
	v_dot4c_i32_i8_e32 v59, v113, v13
	v_dot4c_i32_i8_e32 v60, v117, v13
	v_dot4c_i32_i8_e32 v61, v121, v13
	v_dot4c_i32_i8_e32 v62, v125, v13
	v_dot4c_i32_i8_e32 v63, v129, v13
	v_dot4c_i32_i8_e32 v64, v133, v13
	v_dot4c_i32_i8_e32 v65, v137, v13
	v_dot4c_i32_i8_e32 v66, v141, v13
	v_dot4c_i32_i8_e32 v67, v145, v13
	v_dot4c_i32_i8_e32 v52, v86, v14
	v_dot4c_i32_i8_e32 v53, v90, v14
	v_dot4c_i32_i8_e32 v54, v94, v14
	v_dot4c_i32_i8_e32 v55, v98, v14
	v_dot4c_i32_i8_e32 v56, v102, v14
	v_dot4c_i32_i8_e32 v57, v106, v14
	v_dot4c_i32_i8_e32 v58, v110, v14
	v_dot4c_i32_i8_e32 v59, v114, v14
	v_dot4c_i32_i8_e32 v60, v118, v14
	v_dot4c_i32_i8_e32 v61, v122, v14
	v_dot4c_i32_i8_e32 v62, v126, v14
	v_dot4c_i32_i8_e32 v63, v130, v14
	v_dot4c_i32_i8_e32 v64, v134, v14
	v_dot4c_i32_i8_e32 v65, v138, v14
	v_dot4c_i32_i8_e32 v66, v142, v14
	v_dot4c_i32_i8_e32 v67, v146, v14
	v_dot4c_i32_i8_e32 v52, v87, v15
	v_dot4c_i32_i8_e32 v53, v91, v15
	v_dot4c_i32_i8_e32 v54, v95, v15
	v_dot4c_i32_i8_e32 v55, v99, v15
	v_dot4c_i32_i8_e32 v56, v103, v15
	v_dot4c_i32_i8_e32 v57, v107, v15
	v_dot4c_i32_i8_e32 v58, v111, v15
	v_dot4c_i32_i8_e32 v59, v115, v15
	v_dot4c_i32_i8_e32 v60, v119, v15
	v_dot4c_i32_i8_e32 v61, v123, v15
	v_dot4c_i32_i8_e32 v62, v127, v15
	v_dot4c_i32_i8_e32 v63, v131, v15
	v_dot4c_i32_i8_e32 v64, v135, v15
	v_dot4c_i32_i8_e32 v65, v139, v15
	v_dot4c_i32_i8_e32 v66, v143, v15
	v_dot4c_i32_i8_e32 v67, v147, v15
	ds_write2_b32 v5, v10, v11 offset0:4 offset1:20
	s_waitcnt lgkmcnt(0)
; DI void phase9(const Params& p, char* smem, int rep) {
;     ...
;         for (int q = 0; q < 4; ++q) { const int4 v = *(const int4*)(lw + g * 32 + batch * 16 + q * 4); ida[q * 4] = v.x; ida[q * 4 + 1] = v.y; ida[q * 4 + 2] = v.z; ida[q * 4 + 3] = v.w; }
;         u32x4 rows[16];
; #pragma unroll
;         for (int k = 0; k < 16; ++k) rows[k] = *(const u32x4*)(ub + (size_t)ida[k] * 2048);
;         int part[16];
; #pragma unroll
;         for (int k = 0; k < 16; ++k) {
;           int acc = 0;
; #pragma unroll
;           for (int d = 0; d < 4; ++d) acc = __builtin_amdgcn_sdot4((int)rows[k][d], (int)hq[d], acc, false);
;           part[k] = acc;
;         }
;         int q8[8], q4[4], q2[2];
; #pragma unroll
;         for (int k = 0; k < 8; ++k) q8[k] = (b3 ? part[8 + k] : part[k]) + __shfl_xor(b3 ? part[k] : part[8 + k], 8);
; #pragma unroll
;         for (int k = 0; k < 4; ++k) q4[k] = (b2 ? q8[4 + k] : q8[k]) + __shfl_xor(b2 ? q8[k] : q8[4 + k], 4);
; #pragma unroll
;         for (int k = 0; k < 2; ++k) q2[k] = (b1 ? q4[2 + k] : q4[k]) + __shfl_xor(b1 ? q4[k] : q4[2 + k], 2);
;         const int rr = (b0 ? q2[1] : q2[0]) + __shfl_xor(b0 ? q2[0] : q2[1], 1);
;         PA[((size_t)s * T_ + tok) * 128 + 4 * (batch * 16 + l15) + g] = rr;
	ds_read_b128 v[20:23], v6 offset:16
	ds_read_b128 v[24:27], v6 offset:32
	ds_read_b128 v[28:31], v6 offset:48
	ds_read_b128 v[32:35], v6 offset:64
	ds_read_b128 v[36:39], v6 offset:80
	ds_read_b128 v[40:43], v6 offset:96
	ds_read_b128 v[44:47], v6 offset:112
	ds_read_b128 v[48:51], v6 offset:128
	v_add_u32_dpp v84, v52, v52 row_ror:8 row_mask:0xf bank_mask:0x3
	v_add_u32_dpp v84, v60, v60 row_ror:8 row_mask:0xf bank_mask:0xc
	v_add_u32_dpp v85, v53, v53 row_ror:8 row_mask:0xf bank_mask:0x3
	v_add_u32_dpp v85, v61, v61 row_ror:8 row_mask:0xf bank_mask:0xc
	v_add_u32_dpp v86, v54, v54 row_ror:8 row_mask:0xf bank_mask:0x3
	v_add_u32_dpp v86, v62, v62 row_ror:8 row_mask:0xf bank_mask:0xc
	v_add_u32_dpp v87, v55, v55 row_ror:8 row_mask:0xf bank_mask:0x3
	v_add_u32_dpp v87, v63, v63 row_ror:8 row_mask:0xf bank_mask:0xc
	v_add_u32_dpp v88, v56, v56 row_ror:8 row_mask:0xf bank_mask:0x3
	v_add_u32_dpp v88, v64, v64 row_ror:8 row_mask:0xf bank_mask:0xc
	v_add_u32_dpp v89, v57, v57 row_ror:8 row_mask:0xf bank_mask:0x3
	v_add_u32_dpp v89, v65, v65 row_ror:8 row_mask:0xf bank_mask:0xc
	v_add_u32_dpp v90, v58, v58 row_ror:8 row_mask:0xf bank_mask:0x3
	v_add_u32_dpp v90, v66, v66 row_ror:8 row_mask:0xf bank_mask:0xc
	v_add_u32_dpp v91, v59, v59 row_ror:8 row_mask:0xf bank_mask:0x3
	v_add_u32_dpp v91, v67, v67 row_ror:8 row_mask:0xf bank_mask:0xc
	v_add_u32_dpp v92, v84, v84 row_half_mirror row_mask:0xf bank_mask:0x5
	v_add_u32_dpp v92, v88, v88 row_half_mirror row_mask:0xf bank_mask:0xa
	v_add_u32_dpp v93, v85, v85 row_half_mirror row_mask:0xf bank_mask:0x5
	v_add_u32_dpp v93, v89, v89 row_half_mirror row_mask:0xf bank_mask:0xa
	v_add_u32_dpp v94, v86, v86 row_half_mirror row_mask:0xf bank_mask:0x5
	v_add_u32_dpp v94, v90, v90 row_half_mirror row_mask:0xf bank_mask:0xa
	v_add_u32_dpp v95, v87, v87 row_half_mirror row_mask:0xf bank_mask:0x5
	v_add_u32_dpp v95, v91, v91 row_half_mirror row_mask:0xf bank_mask:0xa
	v_add_u32_dpp v96, v92, v92 quad_perm:[2,3,0,1] row_mask:0xf bank_mask:0xf
	v_add_u32_dpp v97, v93, v93 quad_perm:[2,3,0,1] row_mask:0xf bank_mask:0xf
	v_add_u32_dpp v98, v94, v94 quad_perm:[2,3,0,1] row_mask:0xf bank_mask:0xf
	s_nop 0
	v_add_u32_dpp v99, v95, v95 quad_perm:[2,3,0,1] row_mask:0xf bank_mask:0xf
	v_cndmask_b32_e64 v100, v98, v96, s[2:3]
	v_cndmask_b32_e64 v101, v99, v97, s[2:3]
	v_add_u32_e32 v214, s46, v4
	s_nop 1
	v_add_u32_dpp v102, v100, v100 quad_perm:[1,0,3,2] row_mask:0xf bank_mask:0xf
	v_add_u32_dpp v103, v101, v101 quad_perm:[1,0,3,2] row_mask:0xf bank_mask:0xf
	v_cndmask_b32_e64 v104, v103, v102, s[4:5]
	global_store_dword v214, v104, s[14:15]
	s_waitcnt vmcnt(16)
	v_dot4_i32_i8 v68, v148, v12, 0
	s_waitcnt vmcnt(15)
	v_dot4_i32_i8 v69, v152, v12, 0
	s_waitcnt vmcnt(14)
	v_dot4_i32_i8 v70, v156, v12, 0
	s_waitcnt vmcnt(13)
	v_dot4_i32_i8 v71, v160, v12, 0
	s_waitcnt vmcnt(12)
	v_dot4_i32_i8 v72, v164, v12, 0
	s_waitcnt vmcnt(11)
	v_dot4_i32_i8 v73, v168, v12, 0
	s_waitcnt vmcnt(10)
	v_dot4_i32_i8 v74, v172, v12, 0
	s_waitcnt vmcnt(9)
	v_dot4_i32_i8 v75, v176, v12, 0
	s_waitcnt vmcnt(8)
	v_dot4_i32_i8 v76, v180, v12, 0
	s_waitcnt vmcnt(7)
	v_dot4_i32_i8 v77, v184, v12, 0
	s_waitcnt vmcnt(6)
	v_dot4_i32_i8 v78, v190, v12, 0
	s_waitcnt vmcnt(5)
	v_dot4_i32_i8 v79, v194, v12, 0
	s_waitcnt vmcnt(4)
	v_dot4_i32_i8 v80, v198, v12, 0
	s_waitcnt vmcnt(3)
	v_dot4_i32_i8 v81, v202, v12, 0
	s_waitcnt vmcnt(2)
	v_dot4_i32_i8 v82, v206, v12, 0
	s_waitcnt vmcnt(1)
	v_dot4_i32_i8 v83, v210, v12, 0
	v_dot4c_i32_i8_e32 v68, v149, v13
	v_dot4c_i32_i8_e32 v69, v153, v13
	v_dot4c_i32_i8_e32 v70, v157, v13
	v_dot4c_i32_i8_e32 v71, v161, v13
	v_dot4c_i32_i8_e32 v72, v165, v13
	v_dot4c_i32_i8_e32 v73, v169, v13
	v_dot4c_i32_i8_e32 v74, v173, v13
	v_dot4c_i32_i8_e32 v75, v177, v13
	v_dot4c_i32_i8_e32 v76, v181, v13
	v_dot4c_i32_i8_e32 v77, v185, v13
	v_dot4c_i32_i8_e32 v78, v191, v13
	v_dot4c_i32_i8_e32 v79, v195, v13
	v_dot4c_i32_i8_e32 v80, v199, v13
	v_dot4c_i32_i8_e32 v81, v203, v13
	v_dot4c_i32_i8_e32 v82, v207, v13
	v_dot4c_i32_i8_e32 v83, v211, v13
	v_dot4c_i32_i8_e32 v68, v150, v14
	v_dot4c_i32_i8_e32 v69, v154, v14
	v_dot4c_i32_i8_e32 v70, v158, v14
	v_dot4c_i32_i8_e32 v71, v162, v14
	v_dot4c_i32_i8_e32 v72, v166, v14
	v_dot4c_i32_i8_e32 v73, v170, v14
	v_dot4c_i32_i8_e32 v74, v174, v14
	v_dot4c_i32_i8_e32 v75, v178, v14
	v_dot4c_i32_i8_e32 v76, v182, v14
	v_dot4c_i32_i8_e32 v77, v186, v14
	v_dot4c_i32_i8_e32 v78, v192, v14
	v_dot4c_i32_i8_e32 v79, v196, v14
	v_dot4c_i32_i8_e32 v80, v200, v14
	v_dot4c_i32_i8_e32 v81, v204, v14
	v_dot4c_i32_i8_e32 v82, v208, v14
	v_dot4c_i32_i8_e32 v83, v212, v14
	v_dot4c_i32_i8_e32 v68, v151, v15
	v_dot4c_i32_i8_e32 v69, v155, v15
	v_dot4c_i32_i8_e32 v70, v159, v15
	v_dot4c_i32_i8_e32 v71, v163, v15
	v_dot4c_i32_i8_e32 v72, v167, v15
	v_dot4c_i32_i8_e32 v73, v171, v15
	v_dot4c_i32_i8_e32 v74, v175, v15
	v_dot4c_i32_i8_e32 v75, v179, v15
	v_dot4c_i32_i8_e32 v76, v183, v15
	v_dot4c_i32_i8_e32 v77, v187, v15
	v_dot4c_i32_i8_e32 v78, v193, v15
	v_dot4c_i32_i8_e32 v79, v197, v15
	v_dot4c_i32_i8_e32 v80, v201, v15
	v_dot4c_i32_i8_e32 v81, v205, v15
	v_dot4c_i32_i8_e32 v82, v209, v15
	v_dot4c_i32_i8_e32 v83, v213, v15
	v_add_u32_dpp v148, v68, v68 row_ror:8 row_mask:0xf bank_mask:0x3
	v_add_u32_dpp v148, v76, v76 row_ror:8 row_mask:0xf bank_mask:0xc
	v_add_u32_dpp v149, v69, v69 row_ror:8 row_mask:0xf bank_mask:0x3
	v_add_u32_dpp v149, v77, v77 row_ror:8 row_mask:0xf bank_mask:0xc
	v_add_u32_dpp v150, v70, v70 row_ror:8 row_mask:0xf bank_mask:0x3
	v_add_u32_dpp v150, v78, v78 row_ror:8 row_mask:0xf bank_mask:0xc
	v_add_u32_dpp v151, v71, v71 row_ror:8 row_mask:0xf bank_mask:0x3
; DI void wave_lds_sync() { asm volatile("s_waitcnt lgkmcnt(0)" ::: "memory"); __builtin_amdgcn_wave_barrier(); }
; DI void phase9(const Params& p, char* smem, int rep) {
;     ...
;       const int tok = __builtin_amdgcn_readfirstlane(c * 16 + w * 4 + t);
;       const int i0 = IDS[(size_t)tok * 128 + lane], i1 = IDS[(size_t)tok * 128 + 64 + lane];
;       const u32x4 hq = *(const u32x4*)(H2Q + (size_t)tok * D_ + s * 256 + l15 * 16);
;       wave_lds_sync();
;       lw[(lane & 3) * 32 + (lane >> 2)] = i0;
;       lw[(lane & 3) * 32 + 16 + (lane >> 2)] = i1;
;       wave_lds_sync();
;       const unsigned char* ub = U8 + s * 256 + l15 * 16;
; #pragma unroll
;       for (int batch = 0; batch < 2; ++batch) {
;         int ida[16];
; #pragma unroll
;         for (int q = 0; q < 4; ++q) { const int4 v = *(const int4*)(lw + g * 32 + batch * 16 + q * 4); ida[q * 4] = v.x; ida[q * 4 + 1] = v.y; ida[q * 4 + 2] = v.z; ida[q * 4 + 3] = v.w; }
;         u32x4 rows[16];
; #pragma unroll
;         for (int k = 0; k < 16; ++k) rows[k] = *(const u32x4*)(ub + (size_t)ida[k] * 2048);
;         int part[16];
; #pragma unroll
;         for (int k = 0; k < 16; ++k) {
;           int acc = 0;
; #pragma unroll
;           for (int d = 0; d < 4; ++d) acc = __builtin_amdgcn_sdot4((int)rows[k][d], (int)hq[d], acc, false);
;     ...
;         int q8[8], q4[4], q2[2];
; #pragma unroll
;         for (int k = 0; k < 8; ++k) q8[k] = (b3 ? part[8 + k] : part[k]) + __shfl_xor(b3 ? part[k] : part[8 + k], 8);
; #pragma unroll
;         for (int k = 0; k < 4; ++k) q4[k] = (b2 ? q8[4 + k] : q8[k]) + __shfl_xor(b2 ? q8[k] : q8[4 + k], 4);
; #pragma unroll
;         for (int k = 0; k < 2; ++k) q2[k] = (b1 ? q4[2 + k] : q4[k]) + __shfl_xor(b1 ? q4[k] : q4[2 + k], 2);
;         const int rr = (b0 ? q2[1] : q2[0]) + __shfl_xor(b0 ? q2[0] : q2[1], 1);
;         PA[((size_t)s * T_ + tok) * 128 + 4 * (batch * 16 + l15) + g] = rr;
	v_add_u32_dpp v151, v79, v79 row_ror:8 row_mask:0xf bank_mask:0xc
	v_add_u32_dpp v152, v72, v72 row_ror:8 row_mask:0xf bank_mask:0x3
	v_add_u32_dpp v152, v80, v80 row_ror:8 row_mask:0xf bank_mask:0xc
	v_add_u32_dpp v153, v73, v73 row_ror:8 row_mask:0xf bank_mask:0x3
	v_add_u32_dpp v153, v81, v81 row_ror:8 row_mask:0xf bank_mask:0xc
	v_add_u32_dpp v154, v74, v74 row_ror:8 row_mask:0xf bank_mask:0x3
	v_add_u32_dpp v154, v82, v82 row_ror:8 row_mask:0xf bank_mask:0xc
	v_add_u32_dpp v155, v75, v75 row_ror:8 row_mask:0xf bank_mask:0x3
	v_add_u32_dpp v155, v83, v83 row_ror:8 row_mask:0xf bank_mask:0xc
	v_add_u32_dpp v156, v148, v148 row_half_mirror row_mask:0xf bank_mask:0x5
	v_add_u32_dpp v156, v152, v152 row_half_mirror row_mask:0xf bank_mask:0xa
	v_add_u32_dpp v157, v149, v149 row_half_mirror row_mask:0xf bank_mask:0x5
	v_add_u32_dpp v157, v153, v153 row_half_mirror row_mask:0xf bank_mask:0xa
	v_add_u32_dpp v158, v150, v150 row_half_mirror row_mask:0xf bank_mask:0x5
	v_add_u32_dpp v158, v154, v154 row_half_mirror row_mask:0xf bank_mask:0xa
	v_add_u32_dpp v159, v151, v151 row_half_mirror row_mask:0xf bank_mask:0x5
	v_add_u32_dpp v159, v155, v155 row_half_mirror row_mask:0xf bank_mask:0xa
	v_add_u32_dpp v160, v156, v156 quad_perm:[2,3,0,1] row_mask:0xf bank_mask:0xf
	v_add_u32_dpp v161, v157, v157 quad_perm:[2,3,0,1] row_mask:0xf bank_mask:0xf
	v_add_u32_dpp v162, v158, v158 quad_perm:[2,3,0,1] row_mask:0xf bank_mask:0xf
	s_nop 0
	v_add_u32_dpp v163, v159, v159 quad_perm:[2,3,0,1] row_mask:0xf bank_mask:0xf
	v_cndmask_b32_e64 v164, v162, v160, s[2:3]
	v_cndmask_b32_e64 v165, v163, v161, s[2:3]
	s_nop 0
	s_nop 1
	v_add_u32_dpp v166, v164, v164 quad_perm:[1,0,3,2] row_mask:0xf bank_mask:0xf
	v_add_u32_dpp v167, v165, v165 quad_perm:[1,0,3,2] row_mask:0xf bank_mask:0xf
	v_cndmask_b32_e64 v168, v167, v166, s[4:5]
	global_store_dword v214, v168, s[14:15] offset:256
	s_add_i32 s36, s34, 1
	s_lshl_b32 s46, s36, 9
	s_add_i32 s46, s46, s24
	s_add_i32 s37, s34, 2
	s_lshl_b32 s47, s37, 9
	s_add_u32 s42, s6, s47
	s_addc_u32 s43, s7, 0
	s_lshl_b32 s47, s37, 11
	s_add_u32 s44, s22, s47
	s_addc_u32 s45, s23, 0
	global_load_dword v10, v3, s[42:43]
	global_load_dword v11, v3, s[42:43] offset:256
	global_load_dwordx4 v[12:15], v2, s[44:45]
	s_waitcnt lgkmcnt(0)
	v_lshl_add_u32 v20, v20, 11, v2
	v_lshl_add_u32 v21, v21, 11, v2
	v_lshl_add_u32 v22, v22, 11, v2
	v_lshl_add_u32 v23, v23, 11, v2
	v_lshl_add_u32 v24, v24, 11, v2
	v_lshl_add_u32 v25, v25, 11, v2
	v_lshl_add_u32 v26, v26, 11, v2
	v_lshl_add_u32 v27, v27, 11, v2
	v_lshl_add_u32 v28, v28, 11, v2
	v_lshl_add_u32 v29, v29, 11, v2
	v_lshl_add_u32 v30, v30, 11, v2
	v_lshl_add_u32 v31, v31, 11, v2
	v_lshl_add_u32 v32, v32, 11, v2
	v_lshl_add_u32 v33, v33, 11, v2
	v_lshl_add_u32 v34, v34, 11, v2
	v_lshl_add_u32 v35, v35, 11, v2
	v_lshl_add_u32 v36, v36, 11, v2
	v_lshl_add_u32 v37, v37, 11, v2
	v_lshl_add_u32 v38, v38, 11, v2
	v_lshl_add_u32 v39, v39, 11, v2
	v_lshl_add_u32 v40, v40, 11, v2
	v_lshl_add_u32 v41, v41, 11, v2
	v_lshl_add_u32 v42, v42, 11, v2
	v_lshl_add_u32 v43, v43, 11, v2
	v_lshl_add_u32 v44, v44, 11, v2
	v_lshl_add_u32 v45, v45, 11, v2
	v_lshl_add_u32 v46, v46, 11, v2
	v_lshl_add_u32 v47, v47, 11, v2
	v_lshl_add_u32 v48, v48, 11, v2
	v_lshl_add_u32 v49, v49, 11, v2
	v_lshl_add_u32 v50, v50, 11, v2
	v_lshl_add_u32 v51, v51, 11, v2
	global_load_dwordx4 v[84:87], v20, s[20:21]
	global_load_dwordx4 v[88:91], v21, s[20:21]
	global_load_dwordx4 v[92:95], v22, s[20:21]
	global_load_dwordx4 v[96:99], v23, s[20:21]
	global_load_dwordx4 v[100:103], v24, s[20:21]
	global_load_dwordx4 v[104:107], v25, s[20:21]
	global_load_dwordx4 v[108:111], v26, s[20:21]
	global_load_dwordx4 v[112:115], v27, s[20:21]
	global_load_dwordx4 v[116:119], v28, s[20:21]
	global_load_dwordx4 v[120:123], v29, s[20:21]
	global_load_dwordx4 v[124:127], v30, s[20:21]
	global_load_dwordx4 v[128:131], v31, s[20:21]
	global_load_dwordx4 v[132:135], v32, s[20:21]
	global_load_dwordx4 v[136:139], v33, s[20:21]
	global_load_dwordx4 v[140:143], v34, s[20:21]
	global_load_dwordx4 v[144:147], v35, s[20:21]
	global_load_dwordx4 v[148:151], v36, s[20:21]
	global_load_dwordx4 v[152:155], v37, s[20:21]
	global_load_dwordx4 v[156:159], v38, s[20:21]
	global_load_dwordx4 v[160:163], v39, s[20:21]
	global_load_dwordx4 v[164:167], v40, s[20:21]
	global_load_dwordx4 v[168:171], v41, s[20:21]
	global_load_dwordx4 v[172:175], v42, s[20:21]
	global_load_dwordx4 v[176:179], v43, s[20:21]
	global_load_dwordx4 v[180:183], v44, s[20:21]
	global_load_dwordx4 v[184:187], v45, s[20:21]
	global_load_dwordx4 v[190:193], v46, s[20:21]
	global_load_dwordx4 v[194:197], v47, s[20:21]
	global_load_dwordx4 v[198:201], v48, s[20:21]
	global_load_dwordx4 v[202:205], v49, s[20:21]
	global_load_dwordx4 v[206:209], v50, s[20:21]
	global_load_dwordx4 v[210:213], v51, s[20:21]
	s_waitcnt vmcnt(31)
	v_dot4_i32_i8 v52, v84, v16, 0
	s_waitcnt vmcnt(30)
	v_dot4_i32_i8 v53, v88, v16, 0
	s_waitcnt vmcnt(29)
	v_dot4_i32_i8 v54, v92, v16, 0
	s_waitcnt vmcnt(28)
	v_dot4_i32_i8 v55, v96, v16, 0
	s_waitcnt vmcnt(27)
	v_dot4_i32_i8 v56, v100, v16, 0
	s_waitcnt vmcnt(26)
	v_dot4_i32_i8 v57, v104, v16, 0
	s_waitcnt vmcnt(25)
	v_dot4_i32_i8 v58, v108, v16, 0
	s_waitcnt vmcnt(24)
	v_dot4_i32_i8 v59, v112, v16, 0
	s_waitcnt vmcnt(23)
	v_dot4_i32_i8 v60, v116, v16, 0
	s_waitcnt vmcnt(22)
	v_dot4_i32_i8 v61, v120, v16, 0
	s_waitcnt vmcnt(21)
	v_dot4_i32_i8 v62, v124, v16, 0
	s_waitcnt vmcnt(20)
	v_dot4_i32_i8 v63, v128, v16, 0
	s_waitcnt vmcnt(19)
	v_dot4_i32_i8 v64, v132, v16, 0
	s_waitcnt vmcnt(18)
	v_dot4_i32_i8 v65, v136, v16, 0
	s_waitcnt vmcnt(17)
	v_dot4_i32_i8 v66, v140, v16, 0
	s_waitcnt vmcnt(16)
; DI void phase9(const Params& p, char* smem, int rep) {
;     ...
;         for (int k = 0; k < 16; ++k) rows[k] = *(const u32x4*)(ub + (size_t)ida[k] * 2048);
;         int part[16];
; #pragma unroll
;         for (int k = 0; k < 16; ++k) {
;           int acc = 0;
; #pragma unroll
;           for (int d = 0; d < 4; ++d) acc = __builtin_amdgcn_sdot4((int)rows[k][d], (int)hq[d], acc, false);
;           part[k] = acc;
;         }
;         int q8[8], q4[4], q2[2];
; #pragma unroll
;         for (int k = 0; k < 8; ++k) q8[k] = (b3 ? part[8 + k] : part[k]) + __shfl_xor(b3 ? part[k] : part[8 + k], 8);
; #pragma unroll
;         for (int k = 0; k < 4; ++k) q4[k] = (b2 ? q8[4 + k] : q8[k]) + __shfl_xor(b2 ? q8[k] : q8[4 + k], 4);
; #pragma unroll
;         for (int k = 0; k < 2; ++k) q2[k] = (b1 ? q4[2 + k] : q4[k]) + __shfl_xor(b1 ? q4[k] : q4[2 + k], 2);
;         const int rr = (b0 ? q2[1] : q2[0]) + __shfl_xor(b0 ? q2[0] : q2[1], 1);
;         PA[((size_t)s * T_ + tok) * 128 + 4 * (batch * 16 + l15) + g] = rr;
	v_dot4_i32_i8 v67, v144, v16, 0
	v_dot4c_i32_i8_e32 v52, v85, v17
	v_dot4c_i32_i8_e32 v53, v89, v17
	v_dot4c_i32_i8_e32 v54, v93, v17
	v_dot4c_i32_i8_e32 v55, v97, v17
	v_dot4c_i32_i8_e32 v56, v101, v17
	v_dot4c_i32_i8_e32 v57, v105, v17
	v_dot4c_i32_i8_e32 v58, v109, v17
	v_dot4c_i32_i8_e32 v59, v113, v17
	v_dot4c_i32_i8_e32 v60, v117, v17
	v_dot4c_i32_i8_e32 v61, v121, v17
	v_dot4c_i32_i8_e32 v62, v125, v17
	v_dot4c_i32_i8_e32 v63, v129, v17
	v_dot4c_i32_i8_e32 v64, v133, v17
	v_dot4c_i32_i8_e32 v65, v137, v17
	v_dot4c_i32_i8_e32 v66, v141, v17
	v_dot4c_i32_i8_e32 v67, v145, v17
	v_dot4c_i32_i8_e32 v52, v86, v18
	v_dot4c_i32_i8_e32 v53, v90, v18
	v_dot4c_i32_i8_e32 v54, v94, v18
	v_dot4c_i32_i8_e32 v55, v98, v18
	v_dot4c_i32_i8_e32 v56, v102, v18
	v_dot4c_i32_i8_e32 v57, v106, v18
	v_dot4c_i32_i8_e32 v58, v110, v18
	v_dot4c_i32_i8_e32 v59, v114, v18
	v_dot4c_i32_i8_e32 v60, v118, v18
	v_dot4c_i32_i8_e32 v61, v122, v18
	v_dot4c_i32_i8_e32 v62, v126, v18
	v_dot4c_i32_i8_e32 v63, v130, v18
	v_dot4c_i32_i8_e32 v64, v134, v18
	v_dot4c_i32_i8_e32 v65, v138, v18
	v_dot4c_i32_i8_e32 v66, v142, v18
	v_dot4c_i32_i8_e32 v67, v146, v18
	v_dot4c_i32_i8_e32 v52, v87, v19
	v_dot4c_i32_i8_e32 v53, v91, v19
	v_dot4c_i32_i8_e32 v54, v95, v19
	v_dot4c_i32_i8_e32 v55, v99, v19
	v_dot4c_i32_i8_e32 v56, v103, v19
	v_dot4c_i32_i8_e32 v57, v107, v19
	v_dot4c_i32_i8_e32 v58, v111, v19
	v_dot4c_i32_i8_e32 v59, v115, v19
	v_dot4c_i32_i8_e32 v60, v119, v19
	v_dot4c_i32_i8_e32 v61, v123, v19
	v_dot4c_i32_i8_e32 v62, v127, v19
	v_dot4c_i32_i8_e32 v63, v131, v19
	v_dot4c_i32_i8_e32 v64, v135, v19
	v_dot4c_i32_i8_e32 v65, v139, v19
	v_dot4c_i32_i8_e32 v66, v143, v19
	v_dot4c_i32_i8_e32 v67, v147, v19
	ds_write2_b32 v5, v10, v11 offset0:4 offset1:20
	s_waitcnt lgkmcnt(0)
	ds_read_b128 v[20:23], v6 offset:16
	ds_read_b128 v[24:27], v6 offset:32
	ds_read_b128 v[28:31], v6 offset:48
	ds_read_b128 v[32:35], v6 offset:64
	ds_read_b128 v[36:39], v6 offset:80
	ds_read_b128 v[40:43], v6 offset:96
	ds_read_b128 v[44:47], v6 offset:112
	ds_read_b128 v[48:51], v6 offset:128
	v_add_u32_dpp v84, v52, v52 row_ror:8 row_mask:0xf bank_mask:0x3
	v_add_u32_dpp v84, v60, v60 row_ror:8 row_mask:0xf bank_mask:0xc
	v_add_u32_dpp v85, v53, v53 row_ror:8 row_mask:0xf bank_mask:0x3
	v_add_u32_dpp v85, v61, v61 row_ror:8 row_mask:0xf bank_mask:0xc
	v_add_u32_dpp v86, v54, v54 row_ror:8 row_mask:0xf bank_mask:0x3
	v_add_u32_dpp v86, v62, v62 row_ror:8 row_mask:0xf bank_mask:0xc
	v_add_u32_dpp v87, v55, v55 row_ror:8 row_mask:0xf bank_mask:0x3
	v_add_u32_dpp v87, v63, v63 row_ror:8 row_mask:0xf bank_mask:0xc
	v_add_u32_dpp v88, v56, v56 row_ror:8 row_mask:0xf bank_mask:0x3
	v_add_u32_dpp v88, v64, v64 row_ror:8 row_mask:0xf bank_mask:0xc
	v_add_u32_dpp v89, v57, v57 row_ror:8 row_mask:0xf bank_mask:0x3
	v_add_u32_dpp v89, v65, v65 row_ror:8 row_mask:0xf bank_mask:0xc
	v_add_u32_dpp v90, v58, v58 row_ror:8 row_mask:0xf bank_mask:0x3
	v_add_u32_dpp v90, v66, v66 row_ror:8 row_mask:0xf bank_mask:0xc
	v_add_u32_dpp v91, v59, v59 row_ror:8 row_mask:0xf bank_mask:0x3
	v_add_u32_dpp v91, v67, v67 row_ror:8 row_mask:0xf bank_mask:0xc
	v_add_u32_dpp v92, v84, v84 row_half_mirror row_mask:0xf bank_mask:0x5
	v_add_u32_dpp v92, v88, v88 row_half_mirror row_mask:0xf bank_mask:0xa
	v_add_u32_dpp v93, v85, v85 row_half_mirror row_mask:0xf bank_mask:0x5
	v_add_u32_dpp v93, v89, v89 row_half_mirror row_mask:0xf bank_mask:0xa
	v_add_u32_dpp v94, v86, v86 row_half_mirror row_mask:0xf bank_mask:0x5
	v_add_u32_dpp v94, v90, v90 row_half_mirror row_mask:0xf bank_mask:0xa
	v_add_u32_dpp v95, v87, v87 row_half_mirror row_mask:0xf bank_mask:0x5
	v_add_u32_dpp v95, v91, v91 row_half_mirror row_mask:0xf bank_mask:0xa
	v_add_u32_dpp v96, v92, v92 quad_perm:[2,3,0,1] row_mask:0xf bank_mask:0xf
	v_add_u32_dpp v97, v93, v93 quad_perm:[2,3,0,1] row_mask:0xf bank_mask:0xf
	v_add_u32_dpp v98, v94, v94 quad_perm:[2,3,0,1] row_mask:0xf bank_mask:0xf
	s_nop 0
	v_add_u32_dpp v99, v95, v95 quad_perm:[2,3,0,1] row_mask:0xf bank_mask:0xf
	v_cndmask_b32_e64 v100, v98, v96, s[2:3]
	v_cndmask_b32_e64 v101, v99, v97, s[2:3]
	v_add_u32_e32 v214, s46, v4
	s_nop 1
	v_add_u32_dpp v102, v100, v100 quad_perm:[1,0,3,2] row_mask:0xf bank_mask:0xf
	v_add_u32_dpp v103, v101, v101 quad_perm:[1,0,3,2] row_mask:0xf bank_mask:0xf
	v_cndmask_b32_e64 v104, v103, v102, s[4:5]
	global_store_dword v214, v104, s[14:15]
	s_waitcnt vmcnt(16)
	v_dot4_i32_i8 v68, v148, v16, 0
	s_waitcnt vmcnt(15)
	v_dot4_i32_i8 v69, v152, v16, 0
	s_waitcnt vmcnt(14)
	v_dot4_i32_i8 v70, v156, v16, 0
	s_waitcnt vmcnt(13)
	v_dot4_i32_i8 v71, v160, v16, 0
	s_waitcnt vmcnt(12)
	v_dot4_i32_i8 v72, v164, v16, 0
	s_waitcnt vmcnt(11)
	v_dot4_i32_i8 v73, v168, v16, 0
	s_waitcnt vmcnt(10)
	v_dot4_i32_i8 v74, v172, v16, 0
	s_waitcnt vmcnt(9)
	v_dot4_i32_i8 v75, v176, v16, 0
	s_waitcnt vmcnt(8)
	v_dot4_i32_i8 v76, v180, v16, 0
	s_waitcnt vmcnt(7)
	v_dot4_i32_i8 v77, v184, v16, 0
	s_waitcnt vmcnt(6)
	v_dot4_i32_i8 v78, v190, v16, 0
	s_waitcnt vmcnt(5)
	v_dot4_i32_i8 v79, v194, v16, 0
	s_waitcnt vmcnt(4)
	v_dot4_i32_i8 v80, v198, v16, 0
	s_waitcnt vmcnt(3)
	v_dot4_i32_i8 v81, v202, v16, 0
	s_waitcnt vmcnt(2)
	v_dot4_i32_i8 v82, v206, v16, 0
	s_waitcnt vmcnt(1)
; DI void phase9(const Params& p, char* smem, int rep) {
;     ...
;       const int tok = __builtin_amdgcn_readfirstlane(c * 16 + w * 4 + t);
;       const int i0 = IDS[(size_t)tok * 128 + lane], i1 = IDS[(size_t)tok * 128 + 64 + lane];
;       const u32x4 hq = *(const u32x4*)(H2Q + (size_t)tok * D_ + s * 256 + l15 * 16);
;     ...
;         for (int k = 0; k < 16; ++k) {
;           int acc = 0;
; #pragma unroll
;           for (int d = 0; d < 4; ++d) acc = __builtin_amdgcn_sdot4((int)rows[k][d], (int)hq[d], acc, false);
;           part[k] = acc;
;         }
;         int q8[8], q4[4], q2[2];
; #pragma unroll
;         for (int k = 0; k < 8; ++k) q8[k] = (b3 ? part[8 + k] : part[k]) + __shfl_xor(b3 ? part[k] : part[8 + k], 8);
; #pragma unroll
;         for (int k = 0; k < 4; ++k) q4[k] = (b2 ? q8[4 + k] : q8[k]) + __shfl_xor(b2 ? q8[k] : q8[4 + k], 4);
; #pragma unroll
;         for (int k = 0; k < 2; ++k) q2[k] = (b1 ? q4[2 + k] : q4[k]) + __shfl_xor(b1 ? q4[k] : q4[2 + k], 2);
;         const int rr = (b0 ? q2[1] : q2[0]) + __shfl_xor(b0 ? q2[0] : q2[1], 1);
;         PA[((size_t)s * T_ + tok) * 128 + 4 * (batch * 16 + l15) + g] = rr;
	v_dot4_i32_i8 v83, v210, v16, 0
	v_dot4c_i32_i8_e32 v68, v149, v17
	v_dot4c_i32_i8_e32 v69, v153, v17
	v_dot4c_i32_i8_e32 v70, v157, v17
	v_dot4c_i32_i8_e32 v71, v161, v17
	v_dot4c_i32_i8_e32 v72, v165, v17
	v_dot4c_i32_i8_e32 v73, v169, v17
	v_dot4c_i32_i8_e32 v74, v173, v17
	v_dot4c_i32_i8_e32 v75, v177, v17
	v_dot4c_i32_i8_e32 v76, v181, v17
	v_dot4c_i32_i8_e32 v77, v185, v17
	v_dot4c_i32_i8_e32 v78, v191, v17
	v_dot4c_i32_i8_e32 v79, v195, v17
	v_dot4c_i32_i8_e32 v80, v199, v17
	v_dot4c_i32_i8_e32 v81, v203, v17
	v_dot4c_i32_i8_e32 v82, v207, v17
	v_dot4c_i32_i8_e32 v83, v211, v17
	v_dot4c_i32_i8_e32 v68, v150, v18
	v_dot4c_i32_i8_e32 v69, v154, v18
	v_dot4c_i32_i8_e32 v70, v158, v18
	v_dot4c_i32_i8_e32 v71, v162, v18
	v_dot4c_i32_i8_e32 v72, v166, v18
	v_dot4c_i32_i8_e32 v73, v170, v18
	v_dot4c_i32_i8_e32 v74, v174, v18
	v_dot4c_i32_i8_e32 v75, v178, v18
	v_dot4c_i32_i8_e32 v76, v182, v18
	v_dot4c_i32_i8_e32 v77, v186, v18
	v_dot4c_i32_i8_e32 v78, v192, v18
	v_dot4c_i32_i8_e32 v79, v196, v18
	v_dot4c_i32_i8_e32 v80, v200, v18
	v_dot4c_i32_i8_e32 v81, v204, v18
	v_dot4c_i32_i8_e32 v82, v208, v18
	v_dot4c_i32_i8_e32 v83, v212, v18
	v_dot4c_i32_i8_e32 v68, v151, v19
	v_dot4c_i32_i8_e32 v69, v155, v19
	v_dot4c_i32_i8_e32 v70, v159, v19
	v_dot4c_i32_i8_e32 v71, v163, v19
	v_dot4c_i32_i8_e32 v72, v167, v19
	v_dot4c_i32_i8_e32 v73, v171, v19
	v_dot4c_i32_i8_e32 v74, v175, v19
	v_dot4c_i32_i8_e32 v75, v179, v19
	v_dot4c_i32_i8_e32 v76, v183, v19
	v_dot4c_i32_i8_e32 v77, v187, v19
	v_dot4c_i32_i8_e32 v78, v193, v19
	v_dot4c_i32_i8_e32 v79, v197, v19
	v_dot4c_i32_i8_e32 v80, v201, v19
	v_dot4c_i32_i8_e32 v81, v205, v19
	v_dot4c_i32_i8_e32 v82, v209, v19
	v_dot4c_i32_i8_e32 v83, v213, v19
	v_add_u32_dpp v148, v68, v68 row_ror:8 row_mask:0xf bank_mask:0x3
	v_add_u32_dpp v148, v76, v76 row_ror:8 row_mask:0xf bank_mask:0xc
	v_add_u32_dpp v149, v69, v69 row_ror:8 row_mask:0xf bank_mask:0x3
	v_add_u32_dpp v149, v77, v77 row_ror:8 row_mask:0xf bank_mask:0xc
	v_add_u32_dpp v150, v70, v70 row_ror:8 row_mask:0xf bank_mask:0x3
	v_add_u32_dpp v150, v78, v78 row_ror:8 row_mask:0xf bank_mask:0xc
	v_add_u32_dpp v151, v71, v71 row_ror:8 row_mask:0xf bank_mask:0x3
	v_add_u32_dpp v151, v79, v79 row_ror:8 row_mask:0xf bank_mask:0xc
	v_add_u32_dpp v152, v72, v72 row_ror:8 row_mask:0xf bank_mask:0x3
	v_add_u32_dpp v152, v80, v80 row_ror:8 row_mask:0xf bank_mask:0xc
	v_add_u32_dpp v153, v73, v73 row_ror:8 row_mask:0xf bank_mask:0x3
	v_add_u32_dpp v153, v81, v81 row_ror:8 row_mask:0xf bank_mask:0xc
	v_add_u32_dpp v154, v74, v74 row_ror:8 row_mask:0xf bank_mask:0x3
	v_add_u32_dpp v154, v82, v82 row_ror:8 row_mask:0xf bank_mask:0xc
	v_add_u32_dpp v155, v75, v75 row_ror:8 row_mask:0xf bank_mask:0x3
	v_add_u32_dpp v155, v83, v83 row_ror:8 row_mask:0xf bank_mask:0xc
	v_add_u32_dpp v156, v148, v148 row_half_mirror row_mask:0xf bank_mask:0x5
	v_add_u32_dpp v156, v152, v152 row_half_mirror row_mask:0xf bank_mask:0xa
	v_add_u32_dpp v157, v149, v149 row_half_mirror row_mask:0xf bank_mask:0x5
	v_add_u32_dpp v157, v153, v153 row_half_mirror row_mask:0xf bank_mask:0xa
	v_add_u32_dpp v158, v150, v150 row_half_mirror row_mask:0xf bank_mask:0x5
	v_add_u32_dpp v158, v154, v154 row_half_mirror row_mask:0xf bank_mask:0xa
	v_add_u32_dpp v159, v151, v151 row_half_mirror row_mask:0xf bank_mask:0x5
	v_add_u32_dpp v159, v155, v155 row_half_mirror row_mask:0xf bank_mask:0xa
	v_add_u32_dpp v160, v156, v156 quad_perm:[2,3,0,1] row_mask:0xf bank_mask:0xf
	v_add_u32_dpp v161, v157, v157 quad_perm:[2,3,0,1] row_mask:0xf bank_mask:0xf
	v_add_u32_dpp v162, v158, v158 quad_perm:[2,3,0,1] row_mask:0xf bank_mask:0xf
	s_nop 0
	v_add_u32_dpp v163, v159, v159 quad_perm:[2,3,0,1] row_mask:0xf bank_mask:0xf
	v_cndmask_b32_e64 v164, v162, v160, s[2:3]
	v_cndmask_b32_e64 v165, v163, v161, s[2:3]
	s_nop 0
	s_nop 1
	v_add_u32_dpp v166, v164, v164 quad_perm:[1,0,3,2] row_mask:0xf bank_mask:0xf
	v_add_u32_dpp v167, v165, v165 quad_perm:[1,0,3,2] row_mask:0xf bank_mask:0xf
	v_cndmask_b32_e64 v168, v167, v166, s[4:5]
	global_store_dword v214, v168, s[14:15] offset:256
	s_add_i32 s36, s34, 2
	s_lshl_b32 s46, s36, 9
	s_add_i32 s46, s46, s24
	s_add_i32 s37, s34, 3
	s_lshl_b32 s47, s37, 9
	s_add_u32 s42, s6, s47
	s_addc_u32 s43, s7, 0
	s_lshl_b32 s47, s37, 11
	s_add_u32 s44, s22, s47
	s_addc_u32 s45, s23, 0
	global_load_dword v10, v3, s[42:43]
	global_load_dword v11, v3, s[42:43] offset:256
	global_load_dwordx4 v[16:19], v2, s[44:45]
	s_waitcnt lgkmcnt(0)
; DI void wave_lds_sync() { asm volatile("s_waitcnt lgkmcnt(0)" ::: "memory"); __builtin_amdgcn_wave_barrier(); }
; DI void phase9(const Params& p, char* smem, int rep) {
;     ...
;       wave_lds_sync();
;       lw[(lane & 3) * 32 + (lane >> 2)] = i0;
;       lw[(lane & 3) * 32 + 16 + (lane >> 2)] = i1;
;       wave_lds_sync();
;       const unsigned char* ub = U8 + s * 256 + l15 * 16;
; #pragma unroll
;       for (int batch = 0; batch < 2; ++batch) {
;         int ida[16];
; #pragma unroll
;         for (int q = 0; q < 4; ++q) { const int4 v = *(const int4*)(lw + g * 32 + batch * 16 + q * 4); ida[q * 4] = v.x; ida[q * 4 + 1] = v.y; ida[q * 4 + 2] = v.z; ida[q * 4 + 3] = v.w; }
;         u32x4 rows[16];
; #pragma unroll
;         for (int k = 0; k < 16; ++k) rows[k] = *(const u32x4*)(ub + (size_t)ida[k] * 2048);
;         int part[16];
; #pragma unroll
;         for (int k = 0; k < 16; ++k) {
;           int acc = 0;
; #pragma unroll
;           for (int d = 0; d < 4; ++d) acc = __builtin_amdgcn_sdot4((int)rows[k][d], (int)hq[d], acc, false);
	v_lshl_add_u32 v20, v20, 11, v2
	v_lshl_add_u32 v21, v21, 11, v2
	v_lshl_add_u32 v22, v22, 11, v2
	v_lshl_add_u32 v23, v23, 11, v2
	v_lshl_add_u32 v24, v24, 11, v2
	v_lshl_add_u32 v25, v25, 11, v2
	v_lshl_add_u32 v26, v26, 11, v2
	v_lshl_add_u32 v27, v27, 11, v2
	v_lshl_add_u32 v28, v28, 11, v2
	v_lshl_add_u32 v29, v29, 11, v2
	v_lshl_add_u32 v30, v30, 11, v2
	v_lshl_add_u32 v31, v31, 11, v2
	v_lshl_add_u32 v32, v32, 11, v2
	v_lshl_add_u32 v33, v33, 11, v2
	v_lshl_add_u32 v34, v34, 11, v2
	v_lshl_add_u32 v35, v35, 11, v2
	v_lshl_add_u32 v36, v36, 11, v2
	v_lshl_add_u32 v37, v37, 11, v2
	v_lshl_add_u32 v38, v38, 11, v2
	v_lshl_add_u32 v39, v39, 11, v2
	v_lshl_add_u32 v40, v40, 11, v2
	v_lshl_add_u32 v41, v41, 11, v2
	v_lshl_add_u32 v42, v42, 11, v2
	v_lshl_add_u32 v43, v43, 11, v2
	v_lshl_add_u32 v44, v44, 11, v2
	v_lshl_add_u32 v45, v45, 11, v2
	v_lshl_add_u32 v46, v46, 11, v2
	v_lshl_add_u32 v47, v47, 11, v2
	v_lshl_add_u32 v48, v48, 11, v2
	v_lshl_add_u32 v49, v49, 11, v2
	v_lshl_add_u32 v50, v50, 11, v2
	v_lshl_add_u32 v51, v51, 11, v2
	global_load_dwordx4 v[84:87], v20, s[20:21]
	global_load_dwordx4 v[88:91], v21, s[20:21]
	global_load_dwordx4 v[92:95], v22, s[20:21]
	global_load_dwordx4 v[96:99], v23, s[20:21]
	global_load_dwordx4 v[100:103], v24, s[20:21]
	global_load_dwordx4 v[104:107], v25, s[20:21]
	global_load_dwordx4 v[108:111], v26, s[20:21]
	global_load_dwordx4 v[112:115], v27, s[20:21]
	global_load_dwordx4 v[116:119], v28, s[20:21]
	global_load_dwordx4 v[120:123], v29, s[20:21]
	global_load_dwordx4 v[124:127], v30, s[20:21]
	global_load_dwordx4 v[128:131], v31, s[20:21]
	global_load_dwordx4 v[132:135], v32, s[20:21]
	global_load_dwordx4 v[136:139], v33, s[20:21]
	global_load_dwordx4 v[140:143], v34, s[20:21]
	global_load_dwordx4 v[144:147], v35, s[20:21]
	global_load_dwordx4 v[148:151], v36, s[20:21]
	global_load_dwordx4 v[152:155], v37, s[20:21]
	global_load_dwordx4 v[156:159], v38, s[20:21]
	global_load_dwordx4 v[160:163], v39, s[20:21]
	global_load_dwordx4 v[164:167], v40, s[20:21]
	global_load_dwordx4 v[168:171], v41, s[20:21]
	global_load_dwordx4 v[172:175], v42, s[20:21]
	global_load_dwordx4 v[176:179], v43, s[20:21]
	global_load_dwordx4 v[180:183], v44, s[20:21]
	global_load_dwordx4 v[184:187], v45, s[20:21]
	global_load_dwordx4 v[190:193], v46, s[20:21]
	global_load_dwordx4 v[194:197], v47, s[20:21]
	global_load_dwordx4 v[198:201], v48, s[20:21]
	global_load_dwordx4 v[202:205], v49, s[20:21]
	global_load_dwordx4 v[206:209], v50, s[20:21]
	global_load_dwordx4 v[210:213], v51, s[20:21]
	s_waitcnt vmcnt(31)
	v_dot4_i32_i8 v52, v84, v12, 0
	s_waitcnt vmcnt(30)
	v_dot4_i32_i8 v53, v88, v12, 0
	s_waitcnt vmcnt(29)
	v_dot4_i32_i8 v54, v92, v12, 0
	s_waitcnt vmcnt(28)
	v_dot4_i32_i8 v55, v96, v12, 0
	s_waitcnt vmcnt(27)
	v_dot4_i32_i8 v56, v100, v12, 0
	s_waitcnt vmcnt(26)
	v_dot4_i32_i8 v57, v104, v12, 0
	s_waitcnt vmcnt(25)
	v_dot4_i32_i8 v58, v108, v12, 0
	s_waitcnt vmcnt(24)
	v_dot4_i32_i8 v59, v112, v12, 0
	s_waitcnt vmcnt(23)
	v_dot4_i32_i8 v60, v116, v12, 0
	s_waitcnt vmcnt(22)
	v_dot4_i32_i8 v61, v120, v12, 0
	s_waitcnt vmcnt(21)
	v_dot4_i32_i8 v62, v124, v12, 0
	s_waitcnt vmcnt(20)
	v_dot4_i32_i8 v63, v128, v12, 0
	s_waitcnt vmcnt(19)
	v_dot4_i32_i8 v64, v132, v12, 0
	s_waitcnt vmcnt(18)
	v_dot4_i32_i8 v65, v136, v12, 0
	s_waitcnt vmcnt(17)
	v_dot4_i32_i8 v66, v140, v12, 0
	s_waitcnt vmcnt(16)
	v_dot4_i32_i8 v67, v144, v12, 0
	v_dot4c_i32_i8_e32 v52, v85, v13
	v_dot4c_i32_i8_e32 v53, v89, v13
	v_dot4c_i32_i8_e32 v54, v93, v13
	v_dot4c_i32_i8_e32 v55, v97, v13
	v_dot4c_i32_i8_e32 v56, v101, v13
	v_dot4c_i32_i8_e32 v57, v105, v13
	v_dot4c_i32_i8_e32 v58, v109, v13
	v_dot4c_i32_i8_e32 v59, v113, v13
	v_dot4c_i32_i8_e32 v60, v117, v13
	v_dot4c_i32_i8_e32 v61, v121, v13
	v_dot4c_i32_i8_e32 v62, v125, v13
	v_dot4c_i32_i8_e32 v63, v129, v13
	v_dot4c_i32_i8_e32 v64, v133, v13
	v_dot4c_i32_i8_e32 v65, v137, v13
	v_dot4c_i32_i8_e32 v66, v141, v13
	v_dot4c_i32_i8_e32 v67, v145, v13
	v_dot4c_i32_i8_e32 v52, v86, v14
	v_dot4c_i32_i8_e32 v53, v90, v14
	v_dot4c_i32_i8_e32 v54, v94, v14
	v_dot4c_i32_i8_e32 v55, v98, v14
	v_dot4c_i32_i8_e32 v56, v102, v14
	v_dot4c_i32_i8_e32 v57, v106, v14
	v_dot4c_i32_i8_e32 v58, v110, v14
	v_dot4c_i32_i8_e32 v59, v114, v14
	v_dot4c_i32_i8_e32 v60, v118, v14
	v_dot4c_i32_i8_e32 v61, v122, v14
	v_dot4c_i32_i8_e32 v62, v126, v14
	v_dot4c_i32_i8_e32 v63, v130, v14
	v_dot4c_i32_i8_e32 v64, v134, v14
	v_dot4c_i32_i8_e32 v65, v138, v14
	v_dot4c_i32_i8_e32 v66, v142, v14
	v_dot4c_i32_i8_e32 v67, v146, v14
	v_dot4c_i32_i8_e32 v52, v87, v15
	v_dot4c_i32_i8_e32 v53, v91, v15
	v_dot4c_i32_i8_e32 v54, v95, v15
	v_dot4c_i32_i8_e32 v55, v99, v15
	v_dot4c_i32_i8_e32 v56, v103, v15
	v_dot4c_i32_i8_e32 v57, v107, v15
	v_dot4c_i32_i8_e32 v58, v111, v15
	v_dot4c_i32_i8_e32 v59, v115, v15
	v_dot4c_i32_i8_e32 v60, v119, v15
	v_dot4c_i32_i8_e32 v61, v123, v15
	v_dot4c_i32_i8_e32 v62, v127, v15
	v_dot4c_i32_i8_e32 v63, v131, v15
	v_dot4c_i32_i8_e32 v64, v135, v15
	v_dot4c_i32_i8_e32 v65, v139, v15
	v_dot4c_i32_i8_e32 v66, v143, v15
	v_dot4c_i32_i8_e32 v67, v147, v15
	ds_write2_b32 v5, v10, v11 offset0:4 offset1:20
	s_waitcnt lgkmcnt(0)
; DI void phase9(const Params& p, char* smem, int rep) {
;     ...
;         for (int q = 0; q < 4; ++q) { const int4 v = *(const int4*)(lw + g * 32 + batch * 16 + q * 4); ida[q * 4] = v.x; ida[q * 4 + 1] = v.y; ida[q * 4 + 2] = v.z; ida[q * 4 + 3] = v.w; }
;         u32x4 rows[16];
; #pragma unroll
;         for (int k = 0; k < 16; ++k) rows[k] = *(const u32x4*)(ub + (size_t)ida[k] * 2048);
;         int part[16];
; #pragma unroll
;         for (int k = 0; k < 16; ++k) {
;           int acc = 0;
; #pragma unroll
;           for (int d = 0; d < 4; ++d) acc = __builtin_amdgcn_sdot4((int)rows[k][d], (int)hq[d], acc, false);
;           part[k] = acc;
;         }
;         int q8[8], q4[4], q2[2];
; #pragma unroll
;         for (int k = 0; k < 8; ++k) q8[k] = (b3 ? part[8 + k] : part[k]) + __shfl_xor(b3 ? part[k] : part[8 + k], 8);
; #pragma unroll
;         for (int k = 0; k < 4; ++k) q4[k] = (b2 ? q8[4 + k] : q8[k]) + __shfl_xor(b2 ? q8[k] : q8[4 + k], 4);
; #pragma unroll
;         for (int k = 0; k < 2; ++k) q2[k] = (b1 ? q4[2 + k] : q4[k]) + __shfl_xor(b1 ? q4[k] : q4[2 + k], 2);
;         const int rr = (b0 ? q2[1] : q2[0]) + __shfl_xor(b0 ? q2[0] : q2[1], 1);
;         PA[((size_t)s * T_ + tok) * 128 + 4 * (batch * 16 + l15) + g] = rr;
	ds_read_b128 v[20:23], v6 offset:16
	ds_read_b128 v[24:27], v6 offset:32
	ds_read_b128 v[28:31], v6 offset:48
	ds_read_b128 v[32:35], v6 offset:64
	ds_read_b128 v[36:39], v6 offset:80
	ds_read_b128 v[40:43], v6 offset:96
	ds_read_b128 v[44:47], v6 offset:112
	ds_read_b128 v[48:51], v6 offset:128
	v_add_u32_dpp v84, v52, v52 row_ror:8 row_mask:0xf bank_mask:0x3
	v_add_u32_dpp v84, v60, v60 row_ror:8 row_mask:0xf bank_mask:0xc
	v_add_u32_dpp v85, v53, v53 row_ror:8 row_mask:0xf bank_mask:0x3
	v_add_u32_dpp v85, v61, v61 row_ror:8 row_mask:0xf bank_mask:0xc
	v_add_u32_dpp v86, v54, v54 row_ror:8 row_mask:0xf bank_mask:0x3
	v_add_u32_dpp v86, v62, v62 row_ror:8 row_mask:0xf bank_mask:0xc
	v_add_u32_dpp v87, v55, v55 row_ror:8 row_mask:0xf bank_mask:0x3
	v_add_u32_dpp v87, v63, v63 row_ror:8 row_mask:0xf bank_mask:0xc
	v_add_u32_dpp v88, v56, v56 row_ror:8 row_mask:0xf bank_mask:0x3
	v_add_u32_dpp v88, v64, v64 row_ror:8 row_mask:0xf bank_mask:0xc
	v_add_u32_dpp v89, v57, v57 row_ror:8 row_mask:0xf bank_mask:0x3
	v_add_u32_dpp v89, v65, v65 row_ror:8 row_mask:0xf bank_mask:0xc
	v_add_u32_dpp v90, v58, v58 row_ror:8 row_mask:0xf bank_mask:0x3
	v_add_u32_dpp v90, v66, v66 row_ror:8 row_mask:0xf bank_mask:0xc
	v_add_u32_dpp v91, v59, v59 row_ror:8 row_mask:0xf bank_mask:0x3
	v_add_u32_dpp v91, v67, v67 row_ror:8 row_mask:0xf bank_mask:0xc
	v_add_u32_dpp v92, v84, v84 row_half_mirror row_mask:0xf bank_mask:0x5
	v_add_u32_dpp v92, v88, v88 row_half_mirror row_mask:0xf bank_mask:0xa
	v_add_u32_dpp v93, v85, v85 row_half_mirror row_mask:0xf bank_mask:0x5
	v_add_u32_dpp v93, v89, v89 row_half_mirror row_mask:0xf bank_mask:0xa
	v_add_u32_dpp v94, v86, v86 row_half_mirror row_mask:0xf bank_mask:0x5
	v_add_u32_dpp v94, v90, v90 row_half_mirror row_mask:0xf bank_mask:0xa
	v_add_u32_dpp v95, v87, v87 row_half_mirror row_mask:0xf bank_mask:0x5
	v_add_u32_dpp v95, v91, v91 row_half_mirror row_mask:0xf bank_mask:0xa
	v_add_u32_dpp v96, v92, v92 quad_perm:[2,3,0,1] row_mask:0xf bank_mask:0xf
	v_add_u32_dpp v97, v93, v93 quad_perm:[2,3,0,1] row_mask:0xf bank_mask:0xf
	v_add_u32_dpp v98, v94, v94 quad_perm:[2,3,0,1] row_mask:0xf bank_mask:0xf
	s_nop 0
	v_add_u32_dpp v99, v95, v95 quad_perm:[2,3,0,1] row_mask:0xf bank_mask:0xf
	v_cndmask_b32_e64 v100, v98, v96, s[2:3]
	v_cndmask_b32_e64 v101, v99, v97, s[2:3]
	v_add_u32_e32 v214, s46, v4
	s_nop 1
	v_add_u32_dpp v102, v100, v100 quad_perm:[1,0,3,2] row_mask:0xf bank_mask:0xf
	v_add_u32_dpp v103, v101, v101 quad_perm:[1,0,3,2] row_mask:0xf bank_mask:0xf
	v_cndmask_b32_e64 v104, v103, v102, s[4:5]
	global_store_dword v214, v104, s[14:15]
	s_waitcnt vmcnt(16)
	v_dot4_i32_i8 v68, v148, v12, 0
	s_waitcnt vmcnt(15)
	v_dot4_i32_i8 v69, v152, v12, 0
	s_waitcnt vmcnt(14)
	v_dot4_i32_i8 v70, v156, v12, 0
	s_waitcnt vmcnt(13)
	v_dot4_i32_i8 v71, v160, v12, 0
	s_waitcnt vmcnt(12)
	v_dot4_i32_i8 v72, v164, v12, 0
	s_waitcnt vmcnt(11)
	v_dot4_i32_i8 v73, v168, v12, 0
	s_waitcnt vmcnt(10)
	v_dot4_i32_i8 v74, v172, v12, 0
	s_waitcnt vmcnt(9)
	v_dot4_i32_i8 v75, v176, v12, 0
	s_waitcnt vmcnt(8)
	v_dot4_i32_i8 v76, v180, v12, 0
	s_waitcnt vmcnt(7)
	v_dot4_i32_i8 v77, v184, v12, 0
	s_waitcnt vmcnt(6)
	v_dot4_i32_i8 v78, v190, v12, 0
	s_waitcnt vmcnt(5)
	v_dot4_i32_i8 v79, v194, v12, 0
	s_waitcnt vmcnt(4)
	v_dot4_i32_i8 v80, v198, v12, 0
	s_waitcnt vmcnt(3)
	v_dot4_i32_i8 v81, v202, v12, 0
	s_waitcnt vmcnt(2)
	v_dot4_i32_i8 v82, v206, v12, 0
	s_waitcnt vmcnt(1)
	v_dot4_i32_i8 v83, v210, v12, 0
	v_dot4c_i32_i8_e32 v68, v149, v13
	v_dot4c_i32_i8_e32 v69, v153, v13
	v_dot4c_i32_i8_e32 v70, v157, v13
	v_dot4c_i32_i8_e32 v71, v161, v13
	v_dot4c_i32_i8_e32 v72, v165, v13
	v_dot4c_i32_i8_e32 v73, v169, v13
	v_dot4c_i32_i8_e32 v74, v173, v13
	v_dot4c_i32_i8_e32 v75, v177, v13
	v_dot4c_i32_i8_e32 v76, v181, v13
	v_dot4c_i32_i8_e32 v77, v185, v13
	v_dot4c_i32_i8_e32 v78, v191, v13
	v_dot4c_i32_i8_e32 v79, v195, v13
	v_dot4c_i32_i8_e32 v80, v199, v13
	v_dot4c_i32_i8_e32 v81, v203, v13
	v_dot4c_i32_i8_e32 v82, v207, v13
	v_dot4c_i32_i8_e32 v83, v211, v13
	v_dot4c_i32_i8_e32 v68, v150, v14
	v_dot4c_i32_i8_e32 v69, v154, v14
	v_dot4c_i32_i8_e32 v70, v158, v14
	v_dot4c_i32_i8_e32 v71, v162, v14
	v_dot4c_i32_i8_e32 v72, v166, v14
	v_dot4c_i32_i8_e32 v73, v170, v14
	v_dot4c_i32_i8_e32 v74, v174, v14
	v_dot4c_i32_i8_e32 v75, v178, v14
	v_dot4c_i32_i8_e32 v76, v182, v14
	v_dot4c_i32_i8_e32 v77, v186, v14
	v_dot4c_i32_i8_e32 v78, v192, v14
	v_dot4c_i32_i8_e32 v79, v196, v14
	v_dot4c_i32_i8_e32 v80, v200, v14
	v_dot4c_i32_i8_e32 v81, v204, v14
	v_dot4c_i32_i8_e32 v82, v208, v14
	v_dot4c_i32_i8_e32 v83, v212, v14
	v_dot4c_i32_i8_e32 v68, v151, v15
	v_dot4c_i32_i8_e32 v69, v155, v15
	v_dot4c_i32_i8_e32 v70, v159, v15
	v_dot4c_i32_i8_e32 v71, v163, v15
	v_dot4c_i32_i8_e32 v72, v167, v15
	v_dot4c_i32_i8_e32 v73, v171, v15
	v_dot4c_i32_i8_e32 v74, v175, v15
	v_dot4c_i32_i8_e32 v75, v179, v15
	v_dot4c_i32_i8_e32 v76, v183, v15
	v_dot4c_i32_i8_e32 v77, v187, v15
	v_dot4c_i32_i8_e32 v78, v193, v15
	v_dot4c_i32_i8_e32 v79, v197, v15
	v_dot4c_i32_i8_e32 v80, v201, v15
	v_dot4c_i32_i8_e32 v81, v205, v15
	v_dot4c_i32_i8_e32 v82, v209, v15
	v_dot4c_i32_i8_e32 v83, v213, v15
	v_add_u32_dpp v148, v68, v68 row_ror:8 row_mask:0xf bank_mask:0x3
	v_add_u32_dpp v148, v76, v76 row_ror:8 row_mask:0xf bank_mask:0xc
	v_add_u32_dpp v149, v69, v69 row_ror:8 row_mask:0xf bank_mask:0x3
	v_add_u32_dpp v149, v77, v77 row_ror:8 row_mask:0xf bank_mask:0xc
	v_add_u32_dpp v150, v70, v70 row_ror:8 row_mask:0xf bank_mask:0x3
	v_add_u32_dpp v150, v78, v78 row_ror:8 row_mask:0xf bank_mask:0xc
	v_add_u32_dpp v151, v71, v71 row_ror:8 row_mask:0xf bank_mask:0x3
; DI void wave_lds_sync() { asm volatile("s_waitcnt lgkmcnt(0)" ::: "memory"); __builtin_amdgcn_wave_barrier(); }
; DI void phase9(const Params& p, char* smem, int rep) {
;     ...
;       const int tok = __builtin_amdgcn_readfirstlane(c * 16 + w * 4 + t);
;       const int i0 = IDS[(size_t)tok * 128 + lane], i1 = IDS[(size_t)tok * 128 + 64 + lane];
;       const u32x4 hq = *(const u32x4*)(H2Q + (size_t)tok * D_ + s * 256 + l15 * 16);
;       wave_lds_sync();
;       lw[(lane & 3) * 32 + (lane >> 2)] = i0;
;       lw[(lane & 3) * 32 + 16 + (lane >> 2)] = i1;
;       wave_lds_sync();
;       const unsigned char* ub = U8 + s * 256 + l15 * 16;
; #pragma unroll
;       for (int batch = 0; batch < 2; ++batch) {
;         int ida[16];
; #pragma unroll
;         for (int q = 0; q < 4; ++q) { const int4 v = *(const int4*)(lw + g * 32 + batch * 16 + q * 4); ida[q * 4] = v.x; ida[q * 4 + 1] = v.y; ida[q * 4 + 2] = v.z; ida[q * 4 + 3] = v.w; }
;         u32x4 rows[16];
; #pragma unroll
;         for (int k = 0; k < 16; ++k) rows[k] = *(const u32x4*)(ub + (size_t)ida[k] * 2048);
;         int part[16];
; #pragma unroll
;         for (int k = 0; k < 16; ++k) {
;           int acc = 0;
; #pragma unroll
;           for (int d = 0; d < 4; ++d) acc = __builtin_amdgcn_sdot4((int)rows[k][d], (int)hq[d], acc, false);
;     ...
;         int q8[8], q4[4], q2[2];
; #pragma unroll
;         for (int k = 0; k < 8; ++k) q8[k] = (b3 ? part[8 + k] : part[k]) + __shfl_xor(b3 ? part[k] : part[8 + k], 8);
; #pragma unroll
;         for (int k = 0; k < 4; ++k) q4[k] = (b2 ? q8[4 + k] : q8[k]) + __shfl_xor(b2 ? q8[k] : q8[4 + k], 4);
; #pragma unroll
;         for (int k = 0; k < 2; ++k) q2[k] = (b1 ? q4[2 + k] : q4[k]) + __shfl_xor(b1 ? q4[k] : q4[2 + k], 2);
;         const int rr = (b0 ? q2[1] : q2[0]) + __shfl_xor(b0 ? q2[0] : q2[1], 1);
;         PA[((size_t)s * T_ + tok) * 128 + 4 * (batch * 16 + l15) + g] = rr;
	v_add_u32_dpp v151, v79, v79 row_ror:8 row_mask:0xf bank_mask:0xc
	v_add_u32_dpp v152, v72, v72 row_ror:8 row_mask:0xf bank_mask:0x3
	v_add_u32_dpp v152, v80, v80 row_ror:8 row_mask:0xf bank_mask:0xc
	v_add_u32_dpp v153, v73, v73 row_ror:8 row_mask:0xf bank_mask:0x3
	v_add_u32_dpp v153, v81, v81 row_ror:8 row_mask:0xf bank_mask:0xc
	v_add_u32_dpp v154, v74, v74 row_ror:8 row_mask:0xf bank_mask:0x3
	v_add_u32_dpp v154, v82, v82 row_ror:8 row_mask:0xf bank_mask:0xc
	v_add_u32_dpp v155, v75, v75 row_ror:8 row_mask:0xf bank_mask:0x3
	v_add_u32_dpp v155, v83, v83 row_ror:8 row_mask:0xf bank_mask:0xc
	v_add_u32_dpp v156, v148, v148 row_half_mirror row_mask:0xf bank_mask:0x5
	v_add_u32_dpp v156, v152, v152 row_half_mirror row_mask:0xf bank_mask:0xa
	v_add_u32_dpp v157, v149, v149 row_half_mirror row_mask:0xf bank_mask:0x5
	v_add_u32_dpp v157, v153, v153 row_half_mirror row_mask:0xf bank_mask:0xa
	v_add_u32_dpp v158, v150, v150 row_half_mirror row_mask:0xf bank_mask:0x5
	v_add_u32_dpp v158, v154, v154 row_half_mirror row_mask:0xf bank_mask:0xa
	v_add_u32_dpp v159, v151, v151 row_half_mirror row_mask:0xf bank_mask:0x5
	v_add_u32_dpp v159, v155, v155 row_half_mirror row_mask:0xf bank_mask:0xa
	v_add_u32_dpp v160, v156, v156 quad_perm:[2,3,0,1] row_mask:0xf bank_mask:0xf
	v_add_u32_dpp v161, v157, v157 quad_perm:[2,3,0,1] row_mask:0xf bank_mask:0xf
	v_add_u32_dpp v162, v158, v158 quad_perm:[2,3,0,1] row_mask:0xf bank_mask:0xf
	s_nop 0
	v_add_u32_dpp v163, v159, v159 quad_perm:[2,3,0,1] row_mask:0xf bank_mask:0xf
	v_cndmask_b32_e64 v164, v162, v160, s[2:3]
	v_cndmask_b32_e64 v165, v163, v161, s[2:3]
	s_nop 0
	s_nop 1
	v_add_u32_dpp v166, v164, v164 quad_perm:[1,0,3,2] row_mask:0xf bank_mask:0xf
	v_add_u32_dpp v167, v165, v165 quad_perm:[1,0,3,2] row_mask:0xf bank_mask:0xf
	v_cndmask_b32_e64 v168, v167, v166, s[4:5]
	global_store_dword v214, v168, s[14:15] offset:256
	s_add_i32 s36, s34, 3
	s_lshl_b32 s46, s36, 9
	s_add_i32 s46, s46, s24
	s_add_i32 s37, s34, 4
	s_add_i32 s51, s48, 1
	s_cmp_lt_u32 s51, s49
	s_cselect_b32 s37, s37, 8192
	s_cmp_lt_u32 s37, 8192
	s_cselect_b32 s37, s37, 0
	s_lshl_b32 s47, s37, 9
	s_add_u32 s42, s6, s47
	s_addc_u32 s43, s7, 0
	s_lshl_b32 s47, s37, 11
	s_add_u32 s44, s22, s47
	s_addc_u32 s45, s23, 0
	global_load_dword v10, v3, s[42:43]
	global_load_dword v11, v3, s[42:43] offset:256
	global_load_dwordx4 v[12:15], v2, s[44:45]
	s_waitcnt lgkmcnt(0)
	v_lshl_add_u32 v20, v20, 11, v2
	v_lshl_add_u32 v21, v21, 11, v2
	v_lshl_add_u32 v22, v22, 11, v2
	v_lshl_add_u32 v23, v23, 11, v2
	v_lshl_add_u32 v24, v24, 11, v2
	v_lshl_add_u32 v25, v25, 11, v2
	v_lshl_add_u32 v26, v26, 11, v2
	v_lshl_add_u32 v27, v27, 11, v2
	v_lshl_add_u32 v28, v28, 11, v2
	v_lshl_add_u32 v29, v29, 11, v2
	v_lshl_add_u32 v30, v30, 11, v2
	v_lshl_add_u32 v31, v31, 11, v2
	v_lshl_add_u32 v32, v32, 11, v2
	v_lshl_add_u32 v33, v33, 11, v2
	v_lshl_add_u32 v34, v34, 11, v2
	v_lshl_add_u32 v35, v35, 11, v2
	v_lshl_add_u32 v36, v36, 11, v2
	v_lshl_add_u32 v37, v37, 11, v2
	v_lshl_add_u32 v38, v38, 11, v2
	v_lshl_add_u32 v39, v39, 11, v2
	v_lshl_add_u32 v40, v40, 11, v2
	v_lshl_add_u32 v41, v41, 11, v2
	v_lshl_add_u32 v42, v42, 11, v2
	v_lshl_add_u32 v43, v43, 11, v2
	v_lshl_add_u32 v44, v44, 11, v2
	v_lshl_add_u32 v45, v45, 11, v2
	v_lshl_add_u32 v46, v46, 11, v2
	v_lshl_add_u32 v47, v47, 11, v2
	v_lshl_add_u32 v48, v48, 11, v2
	v_lshl_add_u32 v49, v49, 11, v2
	v_lshl_add_u32 v50, v50, 11, v2
	v_lshl_add_u32 v51, v51, 11, v2
	global_load_dwordx4 v[84:87], v20, s[20:21]
	global_load_dwordx4 v[88:91], v21, s[20:21]
	global_load_dwordx4 v[92:95], v22, s[20:21]
	global_load_dwordx4 v[96:99], v23, s[20:21]
	global_load_dwordx4 v[100:103], v24, s[20:21]
	global_load_dwordx4 v[104:107], v25, s[20:21]
	global_load_dwordx4 v[108:111], v26, s[20:21]
	global_load_dwordx4 v[112:115], v27, s[20:21]
	global_load_dwordx4 v[116:119], v28, s[20:21]
	global_load_dwordx4 v[120:123], v29, s[20:21]
	global_load_dwordx4 v[124:127], v30, s[20:21]
	global_load_dwordx4 v[128:131], v31, s[20:21]
	global_load_dwordx4 v[132:135], v32, s[20:21]
	global_load_dwordx4 v[136:139], v33, s[20:21]
	global_load_dwordx4 v[140:143], v34, s[20:21]
	global_load_dwordx4 v[144:147], v35, s[20:21]
	global_load_dwordx4 v[148:151], v36, s[20:21]
	global_load_dwordx4 v[152:155], v37, s[20:21]
	global_load_dwordx4 v[156:159], v38, s[20:21]
	global_load_dwordx4 v[160:163], v39, s[20:21]
	global_load_dwordx4 v[164:167], v40, s[20:21]
	global_load_dwordx4 v[168:171], v41, s[20:21]
	global_load_dwordx4 v[172:175], v42, s[20:21]
	global_load_dwordx4 v[176:179], v43, s[20:21]
	global_load_dwordx4 v[180:183], v44, s[20:21]
	global_load_dwordx4 v[184:187], v45, s[20:21]
	global_load_dwordx4 v[190:193], v46, s[20:21]
	global_load_dwordx4 v[194:197], v47, s[20:21]
	global_load_dwordx4 v[198:201], v48, s[20:21]
	global_load_dwordx4 v[202:205], v49, s[20:21]
	global_load_dwordx4 v[206:209], v50, s[20:21]
	global_load_dwordx4 v[210:213], v51, s[20:21]
	s_waitcnt vmcnt(31)
	v_dot4_i32_i8 v52, v84, v16, 0
	s_waitcnt vmcnt(30)
	v_dot4_i32_i8 v53, v88, v16, 0
	s_waitcnt vmcnt(29)
	v_dot4_i32_i8 v54, v92, v16, 0
	s_waitcnt vmcnt(28)
	v_dot4_i32_i8 v55, v96, v16, 0
	s_waitcnt vmcnt(27)
	v_dot4_i32_i8 v56, v100, v16, 0
	s_waitcnt vmcnt(26)
	v_dot4_i32_i8 v57, v104, v16, 0
	s_waitcnt vmcnt(25)
	v_dot4_i32_i8 v58, v108, v16, 0
	s_waitcnt vmcnt(24)
	v_dot4_i32_i8 v59, v112, v16, 0
	s_waitcnt vmcnt(23)
	v_dot4_i32_i8 v60, v116, v16, 0
	s_waitcnt vmcnt(22)
	v_dot4_i32_i8 v61, v120, v16, 0
	s_waitcnt vmcnt(21)
	v_dot4_i32_i8 v62, v124, v16, 0
	s_waitcnt vmcnt(20)
	v_dot4_i32_i8 v63, v128, v16, 0
	s_waitcnt vmcnt(19)
; DI void phase9(const Params& p, char* smem, int rep) {
;     ...
;         for (int k = 0; k < 16; ++k) rows[k] = *(const u32x4*)(ub + (size_t)ida[k] * 2048);
;         int part[16];
; #pragma unroll
;         for (int k = 0; k < 16; ++k) {
;           int acc = 0;
; #pragma unroll
;           for (int d = 0; d < 4; ++d) acc = __builtin_amdgcn_sdot4((int)rows[k][d], (int)hq[d], acc, false);
;           part[k] = acc;
;         }
;         int q8[8], q4[4], q2[2];
; #pragma unroll
;         for (int k = 0; k < 8; ++k) q8[k] = (b3 ? part[8 + k] : part[k]) + __shfl_xor(b3 ? part[k] : part[8 + k], 8);
; #pragma unroll
;         for (int k = 0; k < 4; ++k) q4[k] = (b2 ? q8[4 + k] : q8[k]) + __shfl_xor(b2 ? q8[k] : q8[4 + k], 4);
; #pragma unroll
;         for (int k = 0; k < 2; ++k) q2[k] = (b1 ? q4[2 + k] : q4[k]) + __shfl_xor(b1 ? q4[k] : q4[2 + k], 2);
;         const int rr = (b0 ? q2[1] : q2[0]) + __shfl_xor(b0 ? q2[0] : q2[1], 1);
;         PA[((size_t)s * T_ + tok) * 128 + 4 * (batch * 16 + l15) + g] = rr;
	v_dot4_i32_i8 v64, v132, v16, 0
	s_waitcnt vmcnt(18)
	v_dot4_i32_i8 v65, v136, v16, 0
	s_waitcnt vmcnt(17)
	v_dot4_i32_i8 v66, v140, v16, 0
	s_waitcnt vmcnt(16)
	v_dot4_i32_i8 v67, v144, v16, 0
	v_dot4c_i32_i8_e32 v52, v85, v17
	v_dot4c_i32_i8_e32 v53, v89, v17
	v_dot4c_i32_i8_e32 v54, v93, v17
	v_dot4c_i32_i8_e32 v55, v97, v17
	v_dot4c_i32_i8_e32 v56, v101, v17
	v_dot4c_i32_i8_e32 v57, v105, v17
	v_dot4c_i32_i8_e32 v58, v109, v17
	v_dot4c_i32_i8_e32 v59, v113, v17
	v_dot4c_i32_i8_e32 v60, v117, v17
	v_dot4c_i32_i8_e32 v61, v121, v17
	v_dot4c_i32_i8_e32 v62, v125, v17
	v_dot4c_i32_i8_e32 v63, v129, v17
	v_dot4c_i32_i8_e32 v64, v133, v17
	v_dot4c_i32_i8_e32 v65, v137, v17
	v_dot4c_i32_i8_e32 v66, v141, v17
	v_dot4c_i32_i8_e32 v67, v145, v17
	v_dot4c_i32_i8_e32 v52, v86, v18
	v_dot4c_i32_i8_e32 v53, v90, v18
	v_dot4c_i32_i8_e32 v54, v94, v18
	v_dot4c_i32_i8_e32 v55, v98, v18
	v_dot4c_i32_i8_e32 v56, v102, v18
	v_dot4c_i32_i8_e32 v57, v106, v18
	v_dot4c_i32_i8_e32 v58, v110, v18
	v_dot4c_i32_i8_e32 v59, v114, v18
	v_dot4c_i32_i8_e32 v60, v118, v18
	v_dot4c_i32_i8_e32 v61, v122, v18
	v_dot4c_i32_i8_e32 v62, v126, v18
	v_dot4c_i32_i8_e32 v63, v130, v18
	v_dot4c_i32_i8_e32 v64, v134, v18
	v_dot4c_i32_i8_e32 v65, v138, v18
	v_dot4c_i32_i8_e32 v66, v142, v18
	v_dot4c_i32_i8_e32 v67, v146, v18
	v_dot4c_i32_i8_e32 v52, v87, v19
	v_dot4c_i32_i8_e32 v53, v91, v19
	v_dot4c_i32_i8_e32 v54, v95, v19
	v_dot4c_i32_i8_e32 v55, v99, v19
	v_dot4c_i32_i8_e32 v56, v103, v19
	v_dot4c_i32_i8_e32 v57, v107, v19
	v_dot4c_i32_i8_e32 v58, v111, v19
	v_dot4c_i32_i8_e32 v59, v115, v19
	v_dot4c_i32_i8_e32 v60, v119, v19
	v_dot4c_i32_i8_e32 v61, v123, v19
	v_dot4c_i32_i8_e32 v62, v127, v19
	v_dot4c_i32_i8_e32 v63, v131, v19
	v_dot4c_i32_i8_e32 v64, v135, v19
	v_dot4c_i32_i8_e32 v65, v139, v19
	v_dot4c_i32_i8_e32 v66, v143, v19
	v_dot4c_i32_i8_e32 v67, v147, v19
	ds_write2_b32 v5, v10, v11 offset0:4 offset1:20
	s_waitcnt lgkmcnt(0)
	ds_read_b128 v[20:23], v6 offset:16
	ds_read_b128 v[24:27], v6 offset:32
	ds_read_b128 v[28:31], v6 offset:48
	ds_read_b128 v[32:35], v6 offset:64
	ds_read_b128 v[36:39], v6 offset:80
	ds_read_b128 v[40:43], v6 offset:96
	ds_read_b128 v[44:47], v6 offset:112
	ds_read_b128 v[48:51], v6 offset:128
	v_add_u32_dpp v84, v52, v52 row_ror:8 row_mask:0xf bank_mask:0x3
	v_add_u32_dpp v84, v60, v60 row_ror:8 row_mask:0xf bank_mask:0xc
	v_add_u32_dpp v85, v53, v53 row_ror:8 row_mask:0xf bank_mask:0x3
	v_add_u32_dpp v85, v61, v61 row_ror:8 row_mask:0xf bank_mask:0xc
	v_add_u32_dpp v86, v54, v54 row_ror:8 row_mask:0xf bank_mask:0x3
	v_add_u32_dpp v86, v62, v62 row_ror:8 row_mask:0xf bank_mask:0xc
	v_add_u32_dpp v87, v55, v55 row_ror:8 row_mask:0xf bank_mask:0x3
	v_add_u32_dpp v87, v63, v63 row_ror:8 row_mask:0xf bank_mask:0xc
	v_add_u32_dpp v88, v56, v56 row_ror:8 row_mask:0xf bank_mask:0x3
	v_add_u32_dpp v88, v64, v64 row_ror:8 row_mask:0xf bank_mask:0xc
	v_add_u32_dpp v89, v57, v57 row_ror:8 row_mask:0xf bank_mask:0x3
	v_add_u32_dpp v89, v65, v65 row_ror:8 row_mask:0xf bank_mask:0xc
	v_add_u32_dpp v90, v58, v58 row_ror:8 row_mask:0xf bank_mask:0x3
	v_add_u32_dpp v90, v66, v66 row_ror:8 row_mask:0xf bank_mask:0xc
	v_add_u32_dpp v91, v59, v59 row_ror:8 row_mask:0xf bank_mask:0x3
	v_add_u32_dpp v91, v67, v67 row_ror:8 row_mask:0xf bank_mask:0xc
	v_add_u32_dpp v92, v84, v84 row_half_mirror row_mask:0xf bank_mask:0x5
	v_add_u32_dpp v92, v88, v88 row_half_mirror row_mask:0xf bank_mask:0xa
	v_add_u32_dpp v93, v85, v85 row_half_mirror row_mask:0xf bank_mask:0x5
	v_add_u32_dpp v93, v89, v89 row_half_mirror row_mask:0xf bank_mask:0xa
	v_add_u32_dpp v94, v86, v86 row_half_mirror row_mask:0xf bank_mask:0x5
	v_add_u32_dpp v94, v90, v90 row_half_mirror row_mask:0xf bank_mask:0xa
	v_add_u32_dpp v95, v87, v87 row_half_mirror row_mask:0xf bank_mask:0x5
	v_add_u32_dpp v95, v91, v91 row_half_mirror row_mask:0xf bank_mask:0xa
	v_add_u32_dpp v96, v92, v92 quad_perm:[2,3,0,1] row_mask:0xf bank_mask:0xf
	v_add_u32_dpp v97, v93, v93 quad_perm:[2,3,0,1] row_mask:0xf bank_mask:0xf
	v_add_u32_dpp v98, v94, v94 quad_perm:[2,3,0,1] row_mask:0xf bank_mask:0xf
	s_nop 0
	v_add_u32_dpp v99, v95, v95 quad_perm:[2,3,0,1] row_mask:0xf bank_mask:0xf
	v_cndmask_b32_e64 v100, v98, v96, s[2:3]
	v_cndmask_b32_e64 v101, v99, v97, s[2:3]
	v_add_u32_e32 v214, s46, v4
	s_nop 1
	v_add_u32_dpp v102, v100, v100 quad_perm:[1,0,3,2] row_mask:0xf bank_mask:0xf
	v_add_u32_dpp v103, v101, v101 quad_perm:[1,0,3,2] row_mask:0xf bank_mask:0xf
	v_cndmask_b32_e64 v104, v103, v102, s[4:5]
	global_store_dword v214, v104, s[14:15]
	s_waitcnt vmcnt(16)
	v_dot4_i32_i8 v68, v148, v16, 0
	s_waitcnt vmcnt(15)
	v_dot4_i32_i8 v69, v152, v16, 0
	s_waitcnt vmcnt(14)
	v_dot4_i32_i8 v70, v156, v16, 0
	s_waitcnt vmcnt(13)
	v_dot4_i32_i8 v71, v160, v16, 0
	s_waitcnt vmcnt(12)
; DI void phase9(const Params& p, char* smem, int rep) {
;     ...
;         for (int k = 0; k < 16; ++k) {
;           int acc = 0;
; #pragma unroll
;           for (int d = 0; d < 4; ++d) acc = __builtin_amdgcn_sdot4((int)rows[k][d], (int)hq[d], acc, false);
;           part[k] = acc;
;         }
;         int q8[8], q4[4], q2[2];
; #pragma unroll
;         for (int k = 0; k < 8; ++k) q8[k] = (b3 ? part[8 + k] : part[k]) + __shfl_xor(b3 ? part[k] : part[8 + k], 8);
; #pragma unroll
;         for (int k = 0; k < 4; ++k) q4[k] = (b2 ? q8[4 + k] : q8[k]) + __shfl_xor(b2 ? q8[k] : q8[4 + k], 4);
; #pragma unroll
;         for (int k = 0; k < 2; ++k) q2[k] = (b1 ? q4[2 + k] : q4[k]) + __shfl_xor(b1 ? q4[k] : q4[2 + k], 2);
;         const int rr = (b0 ? q2[1] : q2[0]) + __shfl_xor(b0 ? q2[0] : q2[1], 1);
;         PA[((size_t)s * T_ + tok) * 128 + 4 * (batch * 16 + l15) + g] = rr;
;       }
;     }
	v_dot4_i32_i8 v72, v164, v16, 0
	s_waitcnt vmcnt(11)
	v_dot4_i32_i8 v73, v168, v16, 0
	s_waitcnt vmcnt(10)
	v_dot4_i32_i8 v74, v172, v16, 0
	s_waitcnt vmcnt(9)
	v_dot4_i32_i8 v75, v176, v16, 0
	s_waitcnt vmcnt(8)
	v_dot4_i32_i8 v76, v180, v16, 0
	s_waitcnt vmcnt(7)
	v_dot4_i32_i8 v77, v184, v16, 0
	s_waitcnt vmcnt(6)
	v_dot4_i32_i8 v78, v190, v16, 0
	s_waitcnt vmcnt(5)
	v_dot4_i32_i8 v79, v194, v16, 0
	s_waitcnt vmcnt(4)
	v_dot4_i32_i8 v80, v198, v16, 0
	s_waitcnt vmcnt(3)
	v_dot4_i32_i8 v81, v202, v16, 0
	s_waitcnt vmcnt(2)
	v_dot4_i32_i8 v82, v206, v16, 0
	s_waitcnt vmcnt(1)
	v_dot4_i32_i8 v83, v210, v16, 0
	v_dot4c_i32_i8_e32 v68, v149, v17
	v_dot4c_i32_i8_e32 v69, v153, v17
	v_dot4c_i32_i8_e32 v70, v157, v17
	v_dot4c_i32_i8_e32 v71, v161, v17
	v_dot4c_i32_i8_e32 v72, v165, v17
	v_dot4c_i32_i8_e32 v73, v169, v17
	v_dot4c_i32_i8_e32 v74, v173, v17
	v_dot4c_i32_i8_e32 v75, v177, v17
	v_dot4c_i32_i8_e32 v76, v181, v17
	v_dot4c_i32_i8_e32 v77, v185, v17
	v_dot4c_i32_i8_e32 v78, v191, v17
	v_dot4c_i32_i8_e32 v79, v195, v17
	v_dot4c_i32_i8_e32 v80, v199, v17
	v_dot4c_i32_i8_e32 v81, v203, v17
	v_dot4c_i32_i8_e32 v82, v207, v17
	v_dot4c_i32_i8_e32 v83, v211, v17
	v_dot4c_i32_i8_e32 v68, v150, v18
	v_dot4c_i32_i8_e32 v69, v154, v18
	v_dot4c_i32_i8_e32 v70, v158, v18
	v_dot4c_i32_i8_e32 v71, v162, v18
	v_dot4c_i32_i8_e32 v72, v166, v18
	v_dot4c_i32_i8_e32 v73, v170, v18
	v_dot4c_i32_i8_e32 v74, v174, v18
	v_dot4c_i32_i8_e32 v75, v178, v18
	v_dot4c_i32_i8_e32 v76, v182, v18
	v_dot4c_i32_i8_e32 v77, v186, v18
	v_dot4c_i32_i8_e32 v78, v192, v18
	v_dot4c_i32_i8_e32 v79, v196, v18
	v_dot4c_i32_i8_e32 v80, v200, v18
	v_dot4c_i32_i8_e32 v81, v204, v18
	v_dot4c_i32_i8_e32 v82, v208, v18
	v_dot4c_i32_i8_e32 v83, v212, v18
	v_dot4c_i32_i8_e32 v68, v151, v19
	v_dot4c_i32_i8_e32 v69, v155, v19
	v_dot4c_i32_i8_e32 v70, v159, v19
	v_dot4c_i32_i8_e32 v71, v163, v19
	v_dot4c_i32_i8_e32 v72, v167, v19
	v_dot4c_i32_i8_e32 v73, v171, v19
	v_dot4c_i32_i8_e32 v74, v175, v19
	v_dot4c_i32_i8_e32 v75, v179, v19
	v_dot4c_i32_i8_e32 v76, v183, v19
	v_dot4c_i32_i8_e32 v77, v187, v19
	v_dot4c_i32_i8_e32 v78, v193, v19
	v_dot4c_i32_i8_e32 v79, v197, v19
	v_dot4c_i32_i8_e32 v80, v201, v19
	v_dot4c_i32_i8_e32 v81, v205, v19
	v_dot4c_i32_i8_e32 v82, v209, v19
	v_dot4c_i32_i8_e32 v83, v213, v19
	v_add_u32_dpp v148, v68, v68 row_ror:8 row_mask:0xf bank_mask:0x3
	v_add_u32_dpp v148, v76, v76 row_ror:8 row_mask:0xf bank_mask:0xc
	v_add_u32_dpp v149, v69, v69 row_ror:8 row_mask:0xf bank_mask:0x3
	v_add_u32_dpp v149, v77, v77 row_ror:8 row_mask:0xf bank_mask:0xc
	v_add_u32_dpp v150, v70, v70 row_ror:8 row_mask:0xf bank_mask:0x3
	v_add_u32_dpp v150, v78, v78 row_ror:8 row_mask:0xf bank_mask:0xc
	v_add_u32_dpp v151, v71, v71 row_ror:8 row_mask:0xf bank_mask:0x3
	v_add_u32_dpp v151, v79, v79 row_ror:8 row_mask:0xf bank_mask:0xc
	v_add_u32_dpp v152, v72, v72 row_ror:8 row_mask:0xf bank_mask:0x3
	v_add_u32_dpp v152, v80, v80 row_ror:8 row_mask:0xf bank_mask:0xc
	v_add_u32_dpp v153, v73, v73 row_ror:8 row_mask:0xf bank_mask:0x3
	v_add_u32_dpp v153, v81, v81 row_ror:8 row_mask:0xf bank_mask:0xc
	v_add_u32_dpp v154, v74, v74 row_ror:8 row_mask:0xf bank_mask:0x3
	v_add_u32_dpp v154, v82, v82 row_ror:8 row_mask:0xf bank_mask:0xc
	v_add_u32_dpp v155, v75, v75 row_ror:8 row_mask:0xf bank_mask:0x3
	v_add_u32_dpp v155, v83, v83 row_ror:8 row_mask:0xf bank_mask:0xc
	v_add_u32_dpp v156, v148, v148 row_half_mirror row_mask:0xf bank_mask:0x5
	v_add_u32_dpp v156, v152, v152 row_half_mirror row_mask:0xf bank_mask:0xa
	v_add_u32_dpp v157, v149, v149 row_half_mirror row_mask:0xf bank_mask:0x5
	v_add_u32_dpp v157, v153, v153 row_half_mirror row_mask:0xf bank_mask:0xa
	v_add_u32_dpp v158, v150, v150 row_half_mirror row_mask:0xf bank_mask:0x5
	v_add_u32_dpp v158, v154, v154 row_half_mirror row_mask:0xf bank_mask:0xa
	v_add_u32_dpp v159, v151, v151 row_half_mirror row_mask:0xf bank_mask:0x5
	v_add_u32_dpp v159, v155, v155 row_half_mirror row_mask:0xf bank_mask:0xa
	v_add_u32_dpp v160, v156, v156 quad_perm:[2,3,0,1] row_mask:0xf bank_mask:0xf
	v_add_u32_dpp v161, v157, v157 quad_perm:[2,3,0,1] row_mask:0xf bank_mask:0xf
	v_add_u32_dpp v162, v158, v158 quad_perm:[2,3,0,1] row_mask:0xf bank_mask:0xf
	s_nop 0
	v_add_u32_dpp v163, v159, v159 quad_perm:[2,3,0,1] row_mask:0xf bank_mask:0xf
	v_cndmask_b32_e64 v164, v162, v160, s[2:3]
	v_cndmask_b32_e64 v165, v163, v161, s[2:3]
	s_nop 0
	s_nop 1
	v_add_u32_dpp v166, v164, v164 quad_perm:[1,0,3,2] row_mask:0xf bank_mask:0xf
	v_add_u32_dpp v167, v165, v165 quad_perm:[1,0,3,2] row_mask:0xf bank_mask:0xf
	v_cndmask_b32_e64 v168, v167, v166, s[4:5]
	global_store_dword v214, v168, s[14:15] offset:256
	s_add_i32 s48, s48, 1
	s_add_i32 s34, s34, 4
	s_cmp_lt_u32 s48, s49
	s_cbranch_scc0 .Lp9_chunk_done
	s_cmp_lt_u32 s34, 8192
	s_cbranch_scc1 .Lp9_body
	s_branch .Lp9_slice_next
